# k28 + in-proj gates epilogue: sigmoid part first, then the four forget-gate log-sigmoids evaluated at once on 64 lanes (ds_bpermute gather) instead of 4x on 16 lanes
# speedup vs baseline: 1.0195x; 1.0035x over previous
.LBB0_556:
	s_and_saveexec_b64 s[4:5], s[10:11]
	s_xor_b64 s[16:17], exec, s[4:5]
	s_cbranch_execz .LBB0_574
.LBB0_574:
	s_andn2_saveexec_b64 s[4:5], s[16:17]
	s_cbranch_execz .LBB0_576
	v_mul_f32_e32 v0, 0xbfb8aa3b, v186
	v_exp_f32_e32 v186, v0
	v_mul_f32_e32 v0, 0xbfb8aa3b, v190
	v_exp_f32_e32 v190, v0
	v_mul_f32_e32 v0, 0xbfb8aa3b, v187
	v_exp_f32_e32 v187, v0
	v_mul_f32_e32 v0, 0xbfb8aa3b, v191
	v_exp_f32_e32 v191, v0
	v_mul_f32_e32 v0, 0xbfb8aa3b, v188
	v_exp_f32_e32 v188, v0
	v_mul_f32_e32 v0, 0xbfb8aa3b, v192
	v_exp_f32_e32 v192, v0
	v_mul_f32_e32 v0, 0xbfb8aa3b, v189
	v_exp_f32_e32 v189, v0
	v_pk_add_f32 v[186:187], v[186:187], 1.0 op_sel_hi:[1,0]
	v_pk_add_f32 v[190:191], v[190:191], 1.0 op_sel_hi:[1,0]
	v_pk_add_f32 v[188:189], v[188:189], 1.0 op_sel_hi:[1,0]
	s_nop 0
	v_div_scale_f32 v0, s[16:17], v189, v189, 1.0
	v_rcp_f32_e32 v194, v0
	s_nop 0
	v_fma_f32 v195, -v0, v194, 1.0
	v_fmac_f32_e32 v194, v195, v194
	v_div_scale_f32 v195, vcc, 1.0, v189, 1.0
	v_mul_f32_e32 v196, v195, v194
	v_fma_f32 v197, -v0, v196, v195
	v_fmac_f32_e32 v196, v197, v194
	v_fma_f32 v0, -v0, v196, v195
	v_div_fmas_f32 v0, v0, v194, v196
	v_div_fixup_f32 v189, v0, v189, 1.0
	v_div_scale_f32 v0, s[16:17], v188, v188, 1.0
	v_rcp_f32_e32 v194, v0
	s_nop 0
	v_fma_f32 v195, -v0, v194, 1.0
	v_fmac_f32_e32 v194, v195, v194
	v_div_scale_f32 v195, vcc, 1.0, v188, 1.0
	v_mul_f32_e32 v196, v195, v194
	v_fma_f32 v197, -v0, v196, v195
	v_fmac_f32_e32 v196, v197, v194
	v_fma_f32 v0, -v0, v196, v195
	v_div_fmas_f32 v0, v0, v194, v196
	v_div_fixup_f32 v188, v0, v188, 1.0
	v_div_scale_f32 v0, s[16:17], v187, v187, 1.0
	v_rcp_f32_e32 v194, v0
	s_nop 0
	v_fma_f32 v195, -v0, v194, 1.0
	v_fmac_f32_e32 v194, v195, v194
	v_div_scale_f32 v195, vcc, 1.0, v187, 1.0
	v_mul_f32_e32 v196, v195, v194
	v_fma_f32 v197, -v0, v196, v195
	v_fmac_f32_e32 v196, v197, v194
	v_fma_f32 v0, -v0, v196, v195
	v_div_fmas_f32 v0, v0, v194, v196
	v_div_fixup_f32 v187, v0, v187, 1.0
	v_div_scale_f32 v0, s[16:17], v186, v186, 1.0
	v_rcp_f32_e32 v194, v0
	s_nop 0
	v_fma_f32 v195, -v0, v194, 1.0
	v_fmac_f32_e32 v194, v195, v194
	v_div_scale_f32 v195, vcc, 1.0, v186, 1.0
	v_mul_f32_e32 v196, v195, v194
	v_fma_f32 v197, -v0, v196, v195
	v_fmac_f32_e32 v196, v197, v194
	v_fma_f32 v0, -v0, v196, v195
	v_div_fmas_f32 v0, v0, v194, v196
	v_div_fixup_f32 v186, v0, v186, 1.0
	v_mul_f32_e32 v0, 0xbfb8aa3b, v193
	v_exp_f32_e32 v193, v0
	s_nop 0
	v_pk_add_f32 v[192:193], v[192:193], 1.0 op_sel_hi:[1,0]
	s_nop 0
	v_div_scale_f32 v0, s[16:17], v193, v193, 1.0
	v_rcp_f32_e32 v194, v0
	s_nop 0
	v_fma_f32 v195, -v0, v194, 1.0
	v_fmac_f32_e32 v194, v195, v194
	v_div_scale_f32 v195, vcc, 1.0, v193, 1.0
	v_mul_f32_e32 v196, v195, v194
	v_fma_f32 v197, -v0, v196, v195
	v_fmac_f32_e32 v196, v197, v194
	v_fma_f32 v0, -v0, v196, v195
	v_div_fmas_f32 v0, v0, v194, v196
	v_div_fixup_f32 v193, v0, v193, 1.0
	v_div_scale_f32 v0, s[16:17], v192, v192, 1.0
	v_rcp_f32_e32 v194, v0
	s_nop 0
	v_fma_f32 v195, -v0, v194, 1.0
	v_fmac_f32_e32 v194, v195, v194
	v_div_scale_f32 v195, vcc, 1.0, v192, 1.0
	v_mul_f32_e32 v196, v195, v194
	v_fma_f32 v197, -v0, v196, v195
	v_fmac_f32_e32 v196, v197, v194
	v_fma_f32 v0, -v0, v196, v195
	v_div_fmas_f32 v0, v0, v194, v196
	v_div_fixup_f32 v192, v0, v192, 1.0
	v_div_scale_f32 v0, s[16:17], v191, v191, 1.0
	v_rcp_f32_e32 v194, v0
	s_nop 0
	v_fma_f32 v195, -v0, v194, 1.0
	v_fmac_f32_e32 v194, v195, v194
	v_div_scale_f32 v195, vcc, 1.0, v191, 1.0
	v_mul_f32_e32 v196, v195, v194
	v_fma_f32 v197, -v0, v196, v195
	v_fmac_f32_e32 v196, v197, v194
	v_fma_f32 v0, -v0, v196, v195
	v_div_fmas_f32 v0, v0, v194, v196
	v_div_fixup_f32 v191, v0, v191, 1.0
	v_div_scale_f32 v0, s[16:17], v190, v190, 1.0
	v_rcp_f32_e32 v194, v0
	s_movk_i32 s16, 0x60
	v_fma_f32 v195, -v0, v194, 1.0
	v_fmac_f32_e32 v194, v195, v194
	v_div_scale_f32 v195, vcc, 1.0, v190, 1.0
	v_mul_f32_e32 v196, v195, v194
	v_fma_f32 v197, -v0, v196, v195
	v_fmac_f32_e32 v196, v197, v194
	v_fma_f32 v0, -v0, v196, v195
	v_div_fmas_f32 v0, v0, v194, v196
	v_mov_b64_e32 v[194:195], s[20:21]
	v_mad_i64_i32 v[194:195], s[16:17], v226, s16, v[194:195]
	v_lshl_add_u64 v[194:195], v[218:219], 2, v[194:195]
	v_div_fixup_f32 v190, v0, v190, 1.0
	global_store_dwordx4 v[194:195], v[186:189], off
	global_store_dwordx4 v[194:195], v[190:193], off offset:16
.LBB0_576:
	s_or_b64 exec, exec, s[4:5]
	v_and_b32_e32 v194, 15, v240
	v_or_b32_e32 v194, 48, v194
	v_lshlrev_b32_e32 v194, 2, v194
	ds_bpermute_b32 v190, v194, v186
	ds_bpermute_b32 v191, v194, v187
	ds_bpermute_b32 v192, v194, v188
	ds_bpermute_b32 v193, v194, v189
	v_readlane_b32 s4, v254, 26
	v_readlane_b32 s5, v254, 27
	s_nop 4
	s_load_dword s31, s[4:5], 0xc
	s_waitcnt lgkmcnt(0)
	v_add_f32_e32 v0, s31, v193
	s_load_dword s31, s[4:5], 0x0
	s_waitcnt lgkmcnt(0)
	v_add_f32_e32 v195, s31, v190
	v_cmp_eq_u32_e32 vcc, 0, v246
	s_nop 1
	v_cndmask_b32_e32 v0, v0, v195, vcc
	s_load_dword s31, s[4:5], 0x4
	s_waitcnt lgkmcnt(0)
	v_add_f32_e32 v195, s31, v191
	v_cmp_eq_u32_e32 vcc, 1, v246
	s_nop 1
	v_cndmask_b32_e32 v0, v0, v195, vcc
	s_load_dword s31, s[4:5], 0x8
	s_waitcnt lgkmcnt(0)
	v_add_f32_e32 v195, s31, v192
	v_cmp_eq_u32_e32 vcc, 2, v246
	s_nop 1
	v_cndmask_b32_e32 v0, v0, v195, vcc
	v_cmp_nlt_f32_e32 vcc, 0, v0
	s_and_saveexec_b64 s[4:5], vcc
	s_xor_b64 s[4:5], exec, s[4:5]
	s_cbranch_execz .LBB0_559
	v_mul_f32_e32 v186, 0x3fb8aa3b, v0
	v_exp_f32_e32 v186, v186
	s_mov_b32 s31, 0x3f2aaaab
	v_add_f32_e32 v192, 1.0, v186
	v_frexp_mant_f32_e32 v194, v192
	v_cvt_f64_f32_e32 v[190:191], v192
	v_frexp_exp_i32_f64_e32 v190, v[190:191]
	v_cmp_gt_f32_e32 vcc, s31, v194
	v_add_f32_e32 v193, -1.0, v192
	v_sub_f32_e32 v195, v193, v192
	v_subbrev_co_u32_e32 v202, vcc, 0, v190, vcc
	v_sub_u32_e32 v190, 0, v202
	v_sub_f32_e32 v193, v186, v193
	v_add_f32_e32 v195, 1.0, v195
	v_ldexp_f32 v191, v192, v190
	v_add_f32_e32 v193, v193, v195
	v_add_f32_e32 v192, -1.0, v191
	v_add_f32_e32 v194, 1.0, v191
	v_ldexp_f32 v190, v193, v190
	v_add_f32_e32 v193, 1.0, v192
	v_add_f32_e32 v195, -1.0, v194
	v_sub_f32_e32 v193, v191, v193
	v_sub_f32_e32 v191, v191, v195
	v_add_f32_e32 v193, v190, v193
	v_add_f32_e32 v190, v190, v191
	v_add_f32_e32 v203, v194, v190
	v_rcp_f32_e32 v228, v203
	v_sub_f32_e32 v191, v203, v194
	v_sub_f32_e32 v205, v190, v191
	v_add_f32_e32 v191, v192, v193
	v_mul_f32_e32 v230, v191, v228
	v_sub_f32_e32 v190, v191, v192
	v_mul_f32_e32 v192, v203, v230
	v_fma_f32 v194, v230, v203, -v192
	v_fmac_f32_e32 v194, v230, v205
	v_sub_f32_e32 v229, v193, v190
	v_add_f32_e32 v190, v192, v194
	v_sub_f32_e32 v193, v191, v190
	v_pk_add_f32 v[196:197], v[190:191], v[192:193] neg_lo:[0,1] neg_hi:[0,1]
	v_mov_b32_e32 v195, v190
	v_pk_add_f32 v[190:191], v[196:197], v[194:195] neg_lo:[0,1] neg_hi:[0,1]
	s_mov_b32 s31, 0x3f317218
	v_add_f32_e32 v191, v229, v191
	v_add_f32_e32 v190, v190, v191
	v_add_f32_e32 v191, v193, v190
	v_mul_f32_e32 v229, v228, v191
	v_mul_f32_e32 v192, v203, v229
	v_fma_f32 v194, v229, v203, -v192
	v_fmac_f32_e32 v194, v229, v205
	v_sub_f32_e32 v193, v193, v191
	v_add_f32_e32 v203, v190, v193
	v_add_f32_e32 v190, v192, v194
	v_sub_f32_e32 v193, v191, v190
	v_pk_add_f32 v[196:197], v[190:191], v[192:193] neg_lo:[0,1] neg_hi:[0,1]
	v_mov_b32_e32 v195, v190
	v_pk_add_f32 v[190:191], v[196:197], v[194:195] neg_lo:[0,1] neg_hi:[0,1]
	s_nop 0
	v_add_f32_e32 v191, v203, v191
	v_add_f32_e32 v190, v190, v191
	v_add_f32_e32 v191, v230, v229
	v_add_f32_e32 v190, v193, v190
	v_sub_f32_e32 v192, v191, v230
	v_mul_f32_e32 v190, v228, v190
	v_sub_f32_e32 v192, v229, v192
	v_add_f32_e32 v192, v192, v190
	v_add_f32_e32 v194, v191, v192
	v_mul_f32_e32 v195, v194, v194
	v_fmamk_f32 v190, v195, 0x3e9b6dac, v236
	v_fmaak_f32 v205, v195, v190, 0x3f2aaada
	v_cvt_f32_i32_e32 v190, v202
	v_sub_f32_e32 v191, v194, v191
	v_sub_f32_e32 v191, v192, v191
	v_ldexp_f32 v196, v191, 1
	v_mul_f32_e32 v191, v194, v195
	v_ldexp_f32 v193, v194, 1
	v_pk_mul_f32 v[194:195], v[190:191], v[204:205]
	s_nop 0
	v_fma_f32 v192, v190, s31, -v194
	v_fmac_f32_e32 v192, 0xb102e308, v190
	v_pk_add_f32 v[190:191], v[194:195], v[192:193]
	s_mov_b32 s31, 0x7f800000
	v_sub_f32_e32 v193, v191, v193
	v_sub_f32_e32 v193, v195, v193
	v_add_f32_e32 v197, v196, v193
	v_mov_b32_e32 v196, v194
	v_pk_add_f32 v[194:195], v[190:191], v[194:195] neg_lo:[0,1] neg_hi:[0,1]
	v_pk_add_f32 v[228:229], v[190:191], v[196:197]
	v_mov_b32_e32 v193, v190
	v_mov_b32_e32 v195, v229
	v_pk_add_f32 v[230:231], v[192:193], v[194:195] neg_lo:[0,1] neg_hi:[0,1]
	v_pk_add_f32 v[192:193], v[192:193], v[194:195]
	v_mov_b32_e32 v196, v197
	v_pk_add_f32 v[194:195], v[192:193], v[190:191] op_sel:[1,0] op_sel_hi:[0,1] neg_lo:[0,1] neg_hi:[0,1]
	v_pk_add_f32 v[232:233], v[228:229], v[194:195] op_sel_hi:[1,0] neg_lo:[0,1] neg_hi:[0,1]
	v_mov_b32_e32 v228, v229
	v_mov_b32_e32 v229, v193
	v_pk_mov_b32 v[194:195], v[190:191], v[194:195] op_sel:[1,0]
	v_mov_b32_e32 v197, v190
	v_pk_add_f32 v[194:195], v[228:229], v[194:195] neg_lo:[0,1] neg_hi:[0,1]
	v_mov_b32_e32 v232, v230
	v_pk_add_f32 v[190:191], v[196:197], v[194:195] neg_lo:[0,1] neg_hi:[0,1]
	v_mov_b32_e32 v231, v193
	v_pk_add_f32 v[194:195], v[232:233], v[190:191]
	v_cmp_neq_f32_e32 vcc, s31, v186
	v_pk_add_f32 v[196:197], v[194:195], v[194:195] op_sel:[0,1] op_sel_hi:[1,0]
	s_mov_b32 s31, 0x33800000
	v_pk_add_f32 v[192:193], v[192:193], v[196:197] op_sel:[1,0] op_sel_hi:[0,1]
	v_mov_b32_e32 v195, v192
	v_pk_add_f32 v[228:229], v[194:195], v[230:231] neg_lo:[0,1] neg_hi:[0,1]
	v_mov_b32_e32 v191, v196
	v_sub_f32_e32 v193, v194, v228
	v_pk_add_f32 v[190:191], v[190:191], v[228:229] neg_lo:[0,1] neg_hi:[0,1]
	v_sub_f32_e32 v193, v230, v193
	v_add_f32_e32 v190, v190, v193
	v_add_f32_e32 v190, v190, v191
	v_add_f32_e32 v190, v192, v190
	v_cndmask_b32_e32 v190, v237, v190, vcc
	v_cmp_ngt_f32_e32 vcc, -1.0, v186
	s_nop 1
	v_cndmask_b32_e32 v190, v238, v190, vcc
	v_cmp_neq_f32_e32 vcc, -1.0, v186
	s_nop 1
	v_cndmask_b32_e32 v190, v239, v190, vcc
	v_cmp_lt_f32_e64 vcc, |v186|, s31
	s_nop 1
	v_cndmask_b32_e32 v186, v190, v186, vcc
	v_sub_f32_e32 v186, v0, v186

.LBB0_561:
	s_or_b64 exec, exec, s[4:5]
	v_lshlrev_b32_e32 v192, 2, v252
	v_lshlrev_b32_e32 v0, 2, v225
	v_add_u32_e32 v192, v192, v246
	v_ashrrev_i32_e32 v193, 31, v192
	v_lshl_add_u64 v[190:191], s[84:85], 0, v[0:1]
	v_lshlrev_b64 v[194:195], 13, v[192:193]
	v_lshl_add_u64 v[194:195], v[190:191], 0, v[194:195]
	v_readlane_b32 s4, v254, 26
	global_store_dword v[194:195], v186, off
	s_and_b64 vcc, exec, s[12:13]
	s_cbranch_vccnz .LBB0_580

.LBB0_596:
	s_and_saveexec_b64 s[4:5], s[10:11]
	s_xor_b64 s[72:73], exec, s[4:5]
	s_cbranch_execz .LBB0_614
.LBB0_614:
	s_andn2_saveexec_b64 s[4:5], s[72:73]
	s_cbranch_execz .LBB0_616
	v_mul_f32_e32 v0, 0xbfb8aa3b, v178
	v_exp_f32_e32 v178, v0
	v_mul_f32_e32 v0, 0xbfb8aa3b, v182
	v_exp_f32_e32 v182, v0
	v_mul_f32_e32 v0, 0xbfb8aa3b, v179
	v_exp_f32_e32 v179, v0
	v_mul_f32_e32 v0, 0xbfb8aa3b, v183
	v_exp_f32_e32 v183, v0
	v_mul_f32_e32 v0, 0xbfb8aa3b, v180
	v_exp_f32_e32 v180, v0
	v_mul_f32_e32 v0, 0xbfb8aa3b, v184
	v_exp_f32_e32 v184, v0
	v_mul_f32_e32 v0, 0xbfb8aa3b, v181
	v_exp_f32_e32 v181, v0
	v_pk_add_f32 v[178:179], v[178:179], 1.0 op_sel_hi:[1,0]
	v_pk_add_f32 v[182:183], v[182:183], 1.0 op_sel_hi:[1,0]
	s_movk_i32 s31, 0x60
	v_pk_add_f32 v[180:181], v[180:181], 1.0 op_sel_hi:[1,0]
	s_nop 0
	v_div_scale_f32 v0, s[50:51], v181, v181, 1.0
	v_rcp_f32_e32 v186, v0
	s_nop 0
	v_fma_f32 v187, -v0, v186, 1.0
	v_fmac_f32_e32 v186, v187, v186
	v_div_scale_f32 v187, vcc, 1.0, v181, 1.0
	v_mul_f32_e32 v188, v187, v186
	v_fma_f32 v189, -v0, v188, v187
	v_fmac_f32_e32 v188, v189, v186
	v_fma_f32 v0, -v0, v188, v187
	v_div_fmas_f32 v0, v0, v186, v188
	v_div_fixup_f32 v181, v0, v181, 1.0
	v_div_scale_f32 v0, s[50:51], v180, v180, 1.0
	v_rcp_f32_e32 v186, v0
	s_nop 0
	v_fma_f32 v187, -v0, v186, 1.0
	v_fmac_f32_e32 v186, v187, v186
	v_div_scale_f32 v187, vcc, 1.0, v180, 1.0
	v_mul_f32_e32 v188, v187, v186
	v_fma_f32 v189, -v0, v188, v187
	v_fmac_f32_e32 v188, v189, v186
	v_fma_f32 v0, -v0, v188, v187
	v_div_fmas_f32 v0, v0, v186, v188
	v_div_fixup_f32 v180, v0, v180, 1.0
	v_div_scale_f32 v0, s[50:51], v179, v179, 1.0
	v_rcp_f32_e32 v186, v0
	s_nop 0
	v_fma_f32 v187, -v0, v186, 1.0
	v_fmac_f32_e32 v186, v187, v186
	v_div_scale_f32 v187, vcc, 1.0, v179, 1.0
	v_mul_f32_e32 v188, v187, v186
	v_fma_f32 v189, -v0, v188, v187
	v_fmac_f32_e32 v188, v189, v186
	v_fma_f32 v0, -v0, v188, v187
	v_div_fmas_f32 v0, v0, v186, v188
	v_div_fixup_f32 v179, v0, v179, 1.0
	v_div_scale_f32 v0, s[50:51], v178, v178, 1.0
	v_rcp_f32_e32 v186, v0
	s_nop 0
	v_fma_f32 v187, -v0, v186, 1.0
	v_fmac_f32_e32 v186, v187, v186
	v_div_scale_f32 v187, vcc, 1.0, v178, 1.0
	v_mul_f32_e32 v188, v187, v186
	v_fma_f32 v189, -v0, v188, v187
	v_fmac_f32_e32 v188, v189, v186
	v_fma_f32 v0, -v0, v188, v187
	v_div_fmas_f32 v0, v0, v186, v188
	v_div_fixup_f32 v178, v0, v178, 1.0
	v_mul_f32_e32 v0, 0xbfb8aa3b, v185
	v_exp_f32_e32 v185, v0
	s_nop 0
	v_pk_add_f32 v[184:185], v[184:185], 1.0 op_sel_hi:[1,0]
	s_nop 0
	v_div_scale_f32 v0, s[50:51], v185, v185, 1.0
	v_rcp_f32_e32 v186, v0
	s_nop 0
	v_fma_f32 v187, -v0, v186, 1.0
	v_fmac_f32_e32 v186, v187, v186
	v_div_scale_f32 v187, vcc, 1.0, v185, 1.0
	v_mul_f32_e32 v188, v187, v186
	v_fma_f32 v189, -v0, v188, v187
	v_fmac_f32_e32 v188, v189, v186
	v_fma_f32 v0, -v0, v188, v187
	v_div_fmas_f32 v0, v0, v186, v188
	v_div_fixup_f32 v185, v0, v185, 1.0
	v_div_scale_f32 v0, s[50:51], v184, v184, 1.0
	v_rcp_f32_e32 v186, v0
	s_nop 0
	v_fma_f32 v187, -v0, v186, 1.0
	v_fmac_f32_e32 v186, v187, v186
	v_div_scale_f32 v187, vcc, 1.0, v184, 1.0
	v_mul_f32_e32 v188, v187, v186
	v_fma_f32 v189, -v0, v188, v187
	v_fmac_f32_e32 v188, v189, v186
	v_fma_f32 v0, -v0, v188, v187
	v_div_fmas_f32 v0, v0, v186, v188
	v_div_fixup_f32 v184, v0, v184, 1.0
	v_div_scale_f32 v0, s[50:51], v183, v183, 1.0
	v_rcp_f32_e32 v186, v0
	s_nop 0
	v_fma_f32 v187, -v0, v186, 1.0
	v_fmac_f32_e32 v186, v187, v186
	v_div_scale_f32 v187, vcc, 1.0, v183, 1.0
	v_mul_f32_e32 v188, v187, v186
	v_fma_f32 v189, -v0, v188, v187
	v_fmac_f32_e32 v188, v189, v186
	v_fma_f32 v0, -v0, v188, v187
	v_div_fmas_f32 v0, v0, v186, v188
	v_div_fixup_f32 v183, v0, v183, 1.0
	v_div_scale_f32 v0, s[50:51], v182, v182, 1.0
	v_rcp_f32_e32 v186, v0
	s_nop 0
	v_fma_f32 v187, -v0, v186, 1.0
	v_fmac_f32_e32 v186, v187, v186
	v_div_scale_f32 v187, vcc, 1.0, v182, 1.0
	v_mul_f32_e32 v188, v187, v186
	v_fma_f32 v189, -v0, v188, v187
	v_fmac_f32_e32 v188, v189, v186
	v_fma_f32 v0, -v0, v188, v187
	v_div_fmas_f32 v0, v0, v186, v188
	v_mov_b64_e32 v[186:187], s[20:21]
	v_mad_i64_i32 v[186:187], s[50:51], v197, s31, v[186:187]
	v_lshl_add_u64 v[186:187], v[218:219], 2, v[186:187]
	v_div_fixup_f32 v182, v0, v182, 1.0
	global_store_dwordx4 v[186:187], v[178:181], off
	global_store_dwordx4 v[186:187], v[182:185], off offset:16
.LBB0_616:
	s_or_b64 exec, exec, s[4:5]
	v_and_b32_e32 v186, 15, v240
	v_or_b32_e32 v186, 48, v186
	v_lshlrev_b32_e32 v186, 2, v186
	ds_bpermute_b32 v182, v186, v178
	ds_bpermute_b32 v183, v186, v179
	ds_bpermute_b32 v184, v186, v180
	ds_bpermute_b32 v185, v186, v181
	v_readlane_b32 s4, v254, 26
	v_readlane_b32 s5, v254, 27
	s_nop 4
	s_load_dword s31, s[4:5], 0xc
	s_waitcnt lgkmcnt(0)
	v_add_f32_e32 v0, s31, v185
	s_load_dword s31, s[4:5], 0x0
	s_waitcnt lgkmcnt(0)
	v_add_f32_e32 v187, s31, v182
	v_cmp_eq_u32_e32 vcc, 0, v246
	s_nop 1
	v_cndmask_b32_e32 v0, v0, v187, vcc
	s_load_dword s31, s[4:5], 0x4
	s_waitcnt lgkmcnt(0)
	v_add_f32_e32 v187, s31, v183
	v_cmp_eq_u32_e32 vcc, 1, v246
	s_nop 1
	v_cndmask_b32_e32 v0, v0, v187, vcc
	s_load_dword s31, s[4:5], 0x8
	s_waitcnt lgkmcnt(0)
	v_add_f32_e32 v187, s31, v184
	v_cmp_eq_u32_e32 vcc, 2, v246
	s_nop 1
	v_cndmask_b32_e32 v0, v0, v187, vcc
	v_cmp_nlt_f32_e32 vcc, 0, v0
	s_and_saveexec_b64 s[4:5], vcc
	s_xor_b64 s[4:5], exec, s[4:5]
	s_cbranch_execz .LBB0_599
	v_mul_f32_e32 v178, 0x3fb8aa3b, v0
	v_exp_f32_e32 v178, v178
	s_mov_b32 s31, 0x3f2aaaab
	v_add_f32_e32 v184, 1.0, v178
	v_frexp_mant_f32_e32 v186, v184
	v_cvt_f64_f32_e32 v[182:183], v184
	v_frexp_exp_i32_f64_e32 v182, v[182:183]
	v_cmp_gt_f32_e32 vcc, s31, v186
	v_add_f32_e32 v185, -1.0, v184
	v_sub_f32_e32 v187, v185, v184
	v_subbrev_co_u32_e32 v190, vcc, 0, v182, vcc
	v_sub_u32_e32 v182, 0, v190
	v_sub_f32_e32 v185, v178, v185
	v_add_f32_e32 v187, 1.0, v187
	v_ldexp_f32 v183, v184, v182
	v_add_f32_e32 v185, v185, v187
	v_add_f32_e32 v184, -1.0, v183
	v_add_f32_e32 v186, 1.0, v183
	v_ldexp_f32 v182, v185, v182
	v_add_f32_e32 v185, 1.0, v184
	v_add_f32_e32 v187, -1.0, v186
	v_sub_f32_e32 v185, v183, v185
	v_sub_f32_e32 v183, v183, v187
	v_add_f32_e32 v185, v182, v185
	v_add_f32_e32 v182, v182, v183
	v_add_f32_e32 v191, v186, v182
	v_rcp_f32_e32 v193, v191
	v_sub_f32_e32 v183, v191, v186
	v_sub_f32_e32 v192, v182, v183
	v_add_f32_e32 v183, v184, v185
	v_mul_f32_e32 v195, v183, v193
	v_sub_f32_e32 v182, v183, v184
	v_mul_f32_e32 v184, v191, v195
	v_fma_f32 v186, v195, v191, -v184
	v_fmac_f32_e32 v186, v195, v192
	v_sub_f32_e32 v194, v185, v182
	v_add_f32_e32 v182, v184, v186
	v_sub_f32_e32 v185, v183, v182
	v_pk_add_f32 v[188:189], v[182:183], v[184:185] neg_lo:[0,1] neg_hi:[0,1]
	v_mov_b32_e32 v187, v182
	v_pk_add_f32 v[182:183], v[188:189], v[186:187] neg_lo:[0,1] neg_hi:[0,1]
	s_mov_b32 s31, 0x3f317218
	v_add_f32_e32 v183, v194, v183
	v_add_f32_e32 v182, v182, v183
	v_add_f32_e32 v183, v185, v182
	v_mul_f32_e32 v194, v193, v183
	v_mul_f32_e32 v184, v191, v194
	v_fma_f32 v186, v194, v191, -v184
	v_fmac_f32_e32 v186, v194, v192
	v_sub_f32_e32 v185, v185, v183
	v_add_f32_e32 v191, v182, v185
	v_add_f32_e32 v182, v184, v186
	v_sub_f32_e32 v185, v183, v182
	v_pk_add_f32 v[188:189], v[182:183], v[184:185] neg_lo:[0,1] neg_hi:[0,1]
	v_mov_b32_e32 v187, v182
	v_pk_add_f32 v[182:183], v[188:189], v[186:187] neg_lo:[0,1] neg_hi:[0,1]
	s_nop 0
	v_add_f32_e32 v183, v191, v183
	v_add_f32_e32 v182, v182, v183
	v_add_f32_e32 v183, v195, v194
	v_add_f32_e32 v182, v185, v182
	v_sub_f32_e32 v184, v183, v195
	v_mul_f32_e32 v182, v193, v182
	v_sub_f32_e32 v184, v194, v184
	v_add_f32_e32 v184, v184, v182
	v_add_f32_e32 v186, v183, v184
	v_mul_f32_e32 v187, v186, v186
	v_fmamk_f32 v182, v187, 0x3e9b6dac, v236
	v_fmaak_f32 v205, v187, v182, 0x3f2aaada
	v_cvt_f32_i32_e32 v182, v190
	v_sub_f32_e32 v183, v186, v183
	v_sub_f32_e32 v183, v184, v183
	v_ldexp_f32 v188, v183, 1
	v_mul_f32_e32 v183, v186, v187
	v_ldexp_f32 v185, v186, 1
	v_pk_mul_f32 v[186:187], v[182:183], v[204:205]
	s_nop 0
	v_fma_f32 v184, v182, s31, -v186
	v_fmac_f32_e32 v184, 0xb102e308, v182
	v_pk_add_f32 v[182:183], v[186:187], v[184:185]
	s_mov_b32 s31, 0x7f800000
	v_sub_f32_e32 v185, v183, v185
	v_sub_f32_e32 v185, v187, v185
	v_add_f32_e32 v189, v188, v185
	v_mov_b32_e32 v188, v186
	v_pk_add_f32 v[186:187], v[182:183], v[186:187] neg_lo:[0,1] neg_hi:[0,1]
	v_pk_add_f32 v[190:191], v[182:183], v[188:189]
	v_mov_b32_e32 v185, v182
	v_mov_b32_e32 v187, v191
	v_pk_add_f32 v[192:193], v[184:185], v[186:187] neg_lo:[0,1] neg_hi:[0,1]
	v_pk_add_f32 v[184:185], v[184:185], v[186:187]
	v_mov_b32_e32 v188, v189
	v_pk_add_f32 v[186:187], v[184:185], v[182:183] op_sel:[1,0] op_sel_hi:[0,1] neg_lo:[0,1] neg_hi:[0,1]
	v_pk_add_f32 v[194:195], v[190:191], v[186:187] op_sel_hi:[1,0] neg_lo:[0,1] neg_hi:[0,1]
	v_mov_b32_e32 v190, v191
	v_mov_b32_e32 v191, v185
	v_pk_mov_b32 v[186:187], v[182:183], v[186:187] op_sel:[1,0]
	v_mov_b32_e32 v189, v182
	v_pk_add_f32 v[186:187], v[190:191], v[186:187] neg_lo:[0,1] neg_hi:[0,1]
	v_mov_b32_e32 v194, v192
	v_pk_add_f32 v[182:183], v[188:189], v[186:187] neg_lo:[0,1] neg_hi:[0,1]
	v_mov_b32_e32 v193, v185
	v_pk_add_f32 v[186:187], v[194:195], v[182:183]
	v_cmp_neq_f32_e32 vcc, s31, v178
	v_pk_add_f32 v[188:189], v[186:187], v[186:187] op_sel:[0,1] op_sel_hi:[1,0]
	s_mov_b32 s31, 0x33800000
	v_pk_add_f32 v[184:185], v[184:185], v[188:189] op_sel:[1,0] op_sel_hi:[0,1]
	v_mov_b32_e32 v187, v184
	v_pk_add_f32 v[190:191], v[186:187], v[192:193] neg_lo:[0,1] neg_hi:[0,1]
	v_mov_b32_e32 v183, v188
	v_sub_f32_e32 v185, v186, v190
	v_pk_add_f32 v[182:183], v[182:183], v[190:191] neg_lo:[0,1] neg_hi:[0,1]
	v_sub_f32_e32 v185, v192, v185
	v_add_f32_e32 v182, v182, v185
	v_add_f32_e32 v182, v182, v183
	v_add_f32_e32 v182, v184, v182
	v_cndmask_b32_e32 v182, v237, v182, vcc
	v_cmp_ngt_f32_e32 vcc, -1.0, v178
	s_nop 1
	v_cndmask_b32_e32 v182, v238, v182, vcc
	v_cmp_neq_f32_e32 vcc, -1.0, v178
	s_nop 1
	v_cndmask_b32_e32 v182, v239, v182, vcc
	v_cmp_lt_f32_e64 vcc, |v178|, s31
	s_nop 1
	v_cndmask_b32_e32 v178, v182, v178, vcc
	v_sub_f32_e32 v178, v0, v178

.LBB0_601:
	s_or_b64 exec, exec, s[4:5]
	v_lshlrev_b32_e32 v184, 2, v225
	v_lshlrev_b32_e32 v0, 2, v228
	v_add_u32_e32 v184, v184, v246
	v_ashrrev_i32_e32 v185, 31, v184
	v_lshl_add_u64 v[182:183], s[84:85], 0, v[0:1]
	v_lshlrev_b64 v[186:187], 13, v[184:185]
	v_lshl_add_u64 v[186:187], v[182:183], 0, v[186:187]
	v_readlane_b32 s4, v254, 26
	global_store_dword v[186:187], v178, off
	s_and_b64 vcc, exec, s[12:13]
	s_cbranch_vccnz .LBB0_620

.LBB0_636:
	s_and_saveexec_b64 s[4:5], s[10:11]
	s_xor_b64 s[72:73], exec, s[4:5]
	s_cbranch_execz .LBB0_654
.LBB0_654:
	s_andn2_saveexec_b64 s[4:5], s[72:73]
	s_cbranch_execz .LBB0_656
	v_mul_f32_e32 v0, 0xbfb8aa3b, v170
	v_exp_f32_e32 v170, v0
	v_mul_f32_e32 v0, 0xbfb8aa3b, v174
	v_exp_f32_e32 v174, v0
	v_mul_f32_e32 v0, 0xbfb8aa3b, v171
	v_exp_f32_e32 v171, v0
	v_mul_f32_e32 v0, 0xbfb8aa3b, v175
	v_exp_f32_e32 v175, v0
	v_mul_f32_e32 v0, 0xbfb8aa3b, v172
	v_exp_f32_e32 v172, v0
	v_mul_f32_e32 v0, 0xbfb8aa3b, v176
	v_exp_f32_e32 v176, v0
	v_mul_f32_e32 v0, 0xbfb8aa3b, v173
	v_exp_f32_e32 v173, v0
	v_pk_add_f32 v[170:171], v[170:171], 1.0 op_sel_hi:[1,0]
	v_pk_add_f32 v[174:175], v[174:175], 1.0 op_sel_hi:[1,0]
	s_movk_i32 s31, 0x60
	v_pk_add_f32 v[172:173], v[172:173], 1.0 op_sel_hi:[1,0]
	s_nop 0
	v_div_scale_f32 v0, s[50:51], v173, v173, 1.0
	v_rcp_f32_e32 v178, v0
	s_nop 0
	v_fma_f32 v179, -v0, v178, 1.0
	v_fmac_f32_e32 v178, v179, v178
	v_div_scale_f32 v179, vcc, 1.0, v173, 1.0
	v_mul_f32_e32 v180, v179, v178
	v_fma_f32 v181, -v0, v180, v179
	v_fmac_f32_e32 v180, v181, v178
	v_fma_f32 v0, -v0, v180, v179
	v_div_fmas_f32 v0, v0, v178, v180
	v_div_fixup_f32 v173, v0, v173, 1.0
	v_div_scale_f32 v0, s[50:51], v172, v172, 1.0
	v_rcp_f32_e32 v178, v0
	s_nop 0
	v_fma_f32 v179, -v0, v178, 1.0
	v_fmac_f32_e32 v178, v179, v178
	v_div_scale_f32 v179, vcc, 1.0, v172, 1.0
	v_mul_f32_e32 v180, v179, v178
	v_fma_f32 v181, -v0, v180, v179
	v_fmac_f32_e32 v180, v181, v178
	v_fma_f32 v0, -v0, v180, v179
	v_div_fmas_f32 v0, v0, v178, v180
	v_div_fixup_f32 v172, v0, v172, 1.0
	v_div_scale_f32 v0, s[50:51], v171, v171, 1.0
	v_rcp_f32_e32 v178, v0
	s_nop 0
	v_fma_f32 v179, -v0, v178, 1.0
	v_fmac_f32_e32 v178, v179, v178
	v_div_scale_f32 v179, vcc, 1.0, v171, 1.0
	v_mul_f32_e32 v180, v179, v178
	v_fma_f32 v181, -v0, v180, v179
	v_fmac_f32_e32 v180, v181, v178
	v_fma_f32 v0, -v0, v180, v179
	v_div_fmas_f32 v0, v0, v178, v180
	v_div_fixup_f32 v171, v0, v171, 1.0
	v_div_scale_f32 v0, s[50:51], v170, v170, 1.0
	v_rcp_f32_e32 v178, v0
	s_nop 0
	v_fma_f32 v179, -v0, v178, 1.0
	v_fmac_f32_e32 v178, v179, v178
	v_div_scale_f32 v179, vcc, 1.0, v170, 1.0
	v_mul_f32_e32 v180, v179, v178
	v_fma_f32 v181, -v0, v180, v179
	v_fmac_f32_e32 v180, v181, v178
	v_fma_f32 v0, -v0, v180, v179
	v_div_fmas_f32 v0, v0, v178, v180
	v_div_fixup_f32 v170, v0, v170, 1.0
	v_mul_f32_e32 v0, 0xbfb8aa3b, v177
	v_exp_f32_e32 v177, v0
	s_nop 0
	v_pk_add_f32 v[176:177], v[176:177], 1.0 op_sel_hi:[1,0]
	s_nop 0
	v_div_scale_f32 v0, s[50:51], v177, v177, 1.0
	v_rcp_f32_e32 v178, v0
	s_nop 0
	v_fma_f32 v179, -v0, v178, 1.0
	v_fmac_f32_e32 v178, v179, v178
	v_div_scale_f32 v179, vcc, 1.0, v177, 1.0
	v_mul_f32_e32 v180, v179, v178
	v_fma_f32 v181, -v0, v180, v179
	v_fmac_f32_e32 v180, v181, v178
	v_fma_f32 v0, -v0, v180, v179
	v_div_fmas_f32 v0, v0, v178, v180
	v_div_fixup_f32 v177, v0, v177, 1.0
	v_div_scale_f32 v0, s[50:51], v176, v176, 1.0
	v_rcp_f32_e32 v178, v0
	s_nop 0
	v_fma_f32 v179, -v0, v178, 1.0
	v_fmac_f32_e32 v178, v179, v178
	v_div_scale_f32 v179, vcc, 1.0, v176, 1.0
	v_mul_f32_e32 v180, v179, v178
	v_fma_f32 v181, -v0, v180, v179
	v_fmac_f32_e32 v180, v181, v178
	v_fma_f32 v0, -v0, v180, v179
	v_div_fmas_f32 v0, v0, v178, v180
	v_div_fixup_f32 v176, v0, v176, 1.0
	v_div_scale_f32 v0, s[50:51], v175, v175, 1.0
	v_rcp_f32_e32 v178, v0
	s_nop 0
	v_fma_f32 v179, -v0, v178, 1.0
	v_fmac_f32_e32 v178, v179, v178
	v_div_scale_f32 v179, vcc, 1.0, v175, 1.0
	v_mul_f32_e32 v180, v179, v178
	v_fma_f32 v181, -v0, v180, v179
	v_fmac_f32_e32 v180, v181, v178
	v_fma_f32 v0, -v0, v180, v179
	v_div_fmas_f32 v0, v0, v178, v180
	v_div_fixup_f32 v175, v0, v175, 1.0
	v_div_scale_f32 v0, s[50:51], v174, v174, 1.0
	v_rcp_f32_e32 v178, v0
	s_nop 0
	v_fma_f32 v179, -v0, v178, 1.0
	v_fmac_f32_e32 v178, v179, v178
	v_div_scale_f32 v179, vcc, 1.0, v174, 1.0
	v_mul_f32_e32 v180, v179, v178
	v_fma_f32 v181, -v0, v180, v179
	v_fmac_f32_e32 v180, v181, v178
	v_fma_f32 v0, -v0, v180, v179
	v_div_fmas_f32 v0, v0, v178, v180
	v_mov_b64_e32 v[178:179], s[20:21]
	v_mad_i64_i32 v[178:179], s[50:51], v188, s31, v[178:179]
	v_lshl_add_u64 v[178:179], v[218:219], 2, v[178:179]
	v_div_fixup_f32 v174, v0, v174, 1.0
	global_store_dwordx4 v[178:179], v[170:173], off
	global_store_dwordx4 v[178:179], v[174:177], off offset:16
.LBB0_656:
	s_or_b64 exec, exec, s[4:5]
	v_and_b32_e32 v178, 15, v240
	v_or_b32_e32 v178, 48, v178
	v_lshlrev_b32_e32 v178, 2, v178
	ds_bpermute_b32 v174, v178, v170
	ds_bpermute_b32 v175, v178, v171
	ds_bpermute_b32 v176, v178, v172
	ds_bpermute_b32 v177, v178, v173
	v_readlane_b32 s4, v254, 26
	v_readlane_b32 s5, v254, 27
	s_nop 4
	s_load_dword s31, s[4:5], 0xc
	s_waitcnt lgkmcnt(0)
	v_add_f32_e32 v0, s31, v177
	s_load_dword s31, s[4:5], 0x0
	s_waitcnt lgkmcnt(0)
	v_add_f32_e32 v179, s31, v174
	v_cmp_eq_u32_e32 vcc, 0, v246
	s_nop 1
	v_cndmask_b32_e32 v0, v0, v179, vcc
	s_load_dword s31, s[4:5], 0x4
	s_waitcnt lgkmcnt(0)
	v_add_f32_e32 v179, s31, v175
	v_cmp_eq_u32_e32 vcc, 1, v246
	s_nop 1
	v_cndmask_b32_e32 v0, v0, v179, vcc
	s_load_dword s31, s[4:5], 0x8
	s_waitcnt lgkmcnt(0)
	v_add_f32_e32 v179, s31, v176
	v_cmp_eq_u32_e32 vcc, 2, v246
	s_nop 1
	v_cndmask_b32_e32 v0, v0, v179, vcc
	v_cmp_nlt_f32_e32 vcc, 0, v0
	s_and_saveexec_b64 s[4:5], vcc
	s_xor_b64 s[4:5], exec, s[4:5]
	s_cbranch_execz .LBB0_639
	v_mul_f32_e32 v170, 0x3fb8aa3b, v0
	v_exp_f32_e32 v170, v170
	s_mov_b32 s31, 0x3f2aaaab
	v_add_f32_e32 v176, 1.0, v170
	v_frexp_mant_f32_e32 v178, v176
	v_cvt_f64_f32_e32 v[174:175], v176
	v_frexp_exp_i32_f64_e32 v174, v[174:175]
	v_cmp_gt_f32_e32 vcc, s31, v178
	v_add_f32_e32 v177, -1.0, v176
	v_sub_f32_e32 v179, v177, v176
	v_subbrev_co_u32_e32 v182, vcc, 0, v174, vcc
	v_sub_u32_e32 v174, 0, v182
	v_sub_f32_e32 v177, v170, v177
	v_add_f32_e32 v179, 1.0, v179
	v_ldexp_f32 v175, v176, v174
	v_add_f32_e32 v177, v177, v179
	v_add_f32_e32 v176, -1.0, v175
	v_add_f32_e32 v178, 1.0, v175
	v_ldexp_f32 v174, v177, v174
	v_add_f32_e32 v177, 1.0, v176
	v_add_f32_e32 v179, -1.0, v178
	v_sub_f32_e32 v177, v175, v177
	v_sub_f32_e32 v175, v175, v179
	v_add_f32_e32 v177, v174, v177
	v_add_f32_e32 v174, v174, v175
	v_add_f32_e32 v183, v178, v174
	v_rcp_f32_e32 v185, v183
	v_sub_f32_e32 v175, v183, v178
	v_sub_f32_e32 v184, v174, v175
	v_add_f32_e32 v175, v176, v177
	v_mul_f32_e32 v187, v175, v185
	v_sub_f32_e32 v174, v175, v176
	v_mul_f32_e32 v176, v183, v187
	v_fma_f32 v178, v187, v183, -v176
	v_fmac_f32_e32 v178, v187, v184
	v_sub_f32_e32 v186, v177, v174
	v_add_f32_e32 v174, v176, v178
	v_sub_f32_e32 v177, v175, v174
	v_pk_add_f32 v[180:181], v[174:175], v[176:177] neg_lo:[0,1] neg_hi:[0,1]
	v_mov_b32_e32 v179, v174
	v_pk_add_f32 v[174:175], v[180:181], v[178:179] neg_lo:[0,1] neg_hi:[0,1]
	s_mov_b32 s31, 0x3f317218
	v_add_f32_e32 v175, v186, v175
	v_add_f32_e32 v174, v174, v175
	v_add_f32_e32 v175, v177, v174
	v_mul_f32_e32 v186, v185, v175
	v_mul_f32_e32 v176, v183, v186
	v_fma_f32 v178, v186, v183, -v176
	v_fmac_f32_e32 v178, v186, v184
	v_sub_f32_e32 v177, v177, v175
	v_add_f32_e32 v183, v174, v177
	v_add_f32_e32 v174, v176, v178
	v_sub_f32_e32 v177, v175, v174
	v_pk_add_f32 v[180:181], v[174:175], v[176:177] neg_lo:[0,1] neg_hi:[0,1]
	v_mov_b32_e32 v179, v174
	v_pk_add_f32 v[174:175], v[180:181], v[178:179] neg_lo:[0,1] neg_hi:[0,1]
	s_nop 0
	v_add_f32_e32 v175, v183, v175
	v_add_f32_e32 v174, v174, v175
	v_add_f32_e32 v175, v187, v186
	v_add_f32_e32 v174, v177, v174
	v_sub_f32_e32 v176, v175, v187
	v_mul_f32_e32 v174, v185, v174
	v_sub_f32_e32 v176, v186, v176
	v_add_f32_e32 v176, v176, v174
	v_add_f32_e32 v178, v175, v176
	v_mul_f32_e32 v179, v178, v178
	v_fmamk_f32 v174, v179, 0x3e9b6dac, v236
	v_fmaak_f32 v205, v179, v174, 0x3f2aaada
	v_cvt_f32_i32_e32 v174, v182
	v_sub_f32_e32 v175, v178, v175
	v_sub_f32_e32 v175, v176, v175
	v_ldexp_f32 v180, v175, 1
	v_mul_f32_e32 v175, v178, v179
	v_ldexp_f32 v177, v178, 1
	v_pk_mul_f32 v[178:179], v[174:175], v[204:205]
	s_nop 0
	v_fma_f32 v176, v174, s31, -v178
	v_fmac_f32_e32 v176, 0xb102e308, v174
	v_pk_add_f32 v[174:175], v[178:179], v[176:177]
	s_mov_b32 s31, 0x7f800000
	v_sub_f32_e32 v177, v175, v177
	v_sub_f32_e32 v177, v179, v177
	v_add_f32_e32 v181, v180, v177
	v_mov_b32_e32 v180, v178
	v_pk_add_f32 v[178:179], v[174:175], v[178:179] neg_lo:[0,1] neg_hi:[0,1]
	v_pk_add_f32 v[182:183], v[174:175], v[180:181]
	v_mov_b32_e32 v177, v174
	v_mov_b32_e32 v179, v183
	v_pk_add_f32 v[184:185], v[176:177], v[178:179] neg_lo:[0,1] neg_hi:[0,1]
	v_pk_add_f32 v[176:177], v[176:177], v[178:179]
	v_mov_b32_e32 v180, v181
	v_pk_add_f32 v[178:179], v[176:177], v[174:175] op_sel:[1,0] op_sel_hi:[0,1] neg_lo:[0,1] neg_hi:[0,1]
	v_pk_add_f32 v[186:187], v[182:183], v[178:179] op_sel_hi:[1,0] neg_lo:[0,1] neg_hi:[0,1]
	v_mov_b32_e32 v182, v183
	v_mov_b32_e32 v183, v177
	v_pk_mov_b32 v[178:179], v[174:175], v[178:179] op_sel:[1,0]
	v_mov_b32_e32 v181, v174
	v_pk_add_f32 v[178:179], v[182:183], v[178:179] neg_lo:[0,1] neg_hi:[0,1]
	v_mov_b32_e32 v186, v184
	v_pk_add_f32 v[174:175], v[180:181], v[178:179] neg_lo:[0,1] neg_hi:[0,1]
	v_mov_b32_e32 v185, v177
	v_pk_add_f32 v[178:179], v[186:187], v[174:175]
	v_cmp_neq_f32_e32 vcc, s31, v170
	v_pk_add_f32 v[180:181], v[178:179], v[178:179] op_sel:[0,1] op_sel_hi:[1,0]
	s_mov_b32 s31, 0x33800000
	v_pk_add_f32 v[176:177], v[176:177], v[180:181] op_sel:[1,0] op_sel_hi:[0,1]
	v_mov_b32_e32 v179, v176
	v_pk_add_f32 v[182:183], v[178:179], v[184:185] neg_lo:[0,1] neg_hi:[0,1]
	v_mov_b32_e32 v175, v180
	v_sub_f32_e32 v177, v178, v182
	v_pk_add_f32 v[174:175], v[174:175], v[182:183] neg_lo:[0,1] neg_hi:[0,1]
	v_sub_f32_e32 v177, v184, v177
	v_add_f32_e32 v174, v174, v177
	v_add_f32_e32 v174, v174, v175
	v_add_f32_e32 v174, v176, v174
	v_cndmask_b32_e32 v174, v237, v174, vcc
	v_cmp_ngt_f32_e32 vcc, -1.0, v170
	s_nop 1
	v_cndmask_b32_e32 v174, v238, v174, vcc
	v_cmp_neq_f32_e32 vcc, -1.0, v170
	s_nop 1
	v_cndmask_b32_e32 v174, v239, v174, vcc
	v_cmp_lt_f32_e64 vcc, |v170|, s31
	s_nop 1
	v_cndmask_b32_e32 v170, v174, v170, vcc
	v_sub_f32_e32 v170, v0, v170

.LBB0_641:
	s_or_b64 exec, exec, s[4:5]
	v_lshlrev_b32_e32 v176, 2, v189
	v_lshlrev_b32_e32 v0, 2, v190
	v_add_u32_e32 v176, v176, v246
	v_ashrrev_i32_e32 v177, 31, v176
	v_lshl_add_u64 v[174:175], s[84:85], 0, v[0:1]
	v_lshlrev_b64 v[178:179], 13, v[176:177]
	v_lshl_add_u64 v[178:179], v[174:175], 0, v[178:179]
	v_readlane_b32 s4, v254, 26
	global_store_dword v[178:179], v170, off
	s_and_b64 vcc, exec, s[12:13]
	s_cbranch_vccnz .LBB0_660

.LBB0_677:
	s_and_saveexec_b64 s[4:5], s[10:11]
	s_xor_b64 s[72:73], exec, s[4:5]
	s_cbranch_execz .LBB0_695
.LBB0_695:
	s_andn2_saveexec_b64 s[4:5], s[72:73]
	s_cbranch_execz .LBB0_697
	v_mul_f32_e32 v0, 0xbfb8aa3b, v146
	v_exp_f32_e32 v146, v0
	v_mul_f32_e32 v0, 0xbfb8aa3b, v166
	v_exp_f32_e32 v166, v0
	v_mul_f32_e32 v0, 0xbfb8aa3b, v147
	v_exp_f32_e32 v147, v0
	v_mul_f32_e32 v0, 0xbfb8aa3b, v167
	v_exp_f32_e32 v167, v0
	v_mul_f32_e32 v0, 0xbfb8aa3b, v148
	v_exp_f32_e32 v148, v0
	v_mul_f32_e32 v0, 0xbfb8aa3b, v168
	v_exp_f32_e32 v168, v0
	v_mul_f32_e32 v0, 0xbfb8aa3b, v149
	v_exp_f32_e32 v149, v0
	v_pk_add_f32 v[146:147], v[146:147], 1.0 op_sel_hi:[1,0]
	v_pk_add_f32 v[166:167], v[166:167], 1.0 op_sel_hi:[1,0]
	s_movk_i32 s31, 0x60
	v_pk_add_f32 v[148:149], v[148:149], 1.0 op_sel_hi:[1,0]
	s_nop 0
	v_div_scale_f32 v0, s[50:51], v149, v149, 1.0
	v_rcp_f32_e32 v170, v0
	s_nop 0
	v_fma_f32 v171, -v0, v170, 1.0
	v_fmac_f32_e32 v170, v171, v170
	v_div_scale_f32 v171, vcc, 1.0, v149, 1.0
	v_mul_f32_e32 v172, v171, v170
	v_fma_f32 v173, -v0, v172, v171
	v_fmac_f32_e32 v172, v173, v170
	v_fma_f32 v0, -v0, v172, v171
	v_div_fmas_f32 v0, v0, v170, v172
	v_div_fixup_f32 v149, v0, v149, 1.0
	v_div_scale_f32 v0, s[50:51], v148, v148, 1.0
	v_rcp_f32_e32 v170, v0
	s_nop 0
	v_fma_f32 v171, -v0, v170, 1.0
	v_fmac_f32_e32 v170, v171, v170
	v_div_scale_f32 v171, vcc, 1.0, v148, 1.0
	v_mul_f32_e32 v172, v171, v170
	v_fma_f32 v173, -v0, v172, v171
	v_fmac_f32_e32 v172, v173, v170
	v_fma_f32 v0, -v0, v172, v171
	v_div_fmas_f32 v0, v0, v170, v172
	v_div_fixup_f32 v148, v0, v148, 1.0
	v_div_scale_f32 v0, s[50:51], v147, v147, 1.0
	v_rcp_f32_e32 v170, v0
	s_nop 0
	v_fma_f32 v171, -v0, v170, 1.0
	v_fmac_f32_e32 v170, v171, v170
	v_div_scale_f32 v171, vcc, 1.0, v147, 1.0
	v_mul_f32_e32 v172, v171, v170
	v_fma_f32 v173, -v0, v172, v171
	v_fmac_f32_e32 v172, v173, v170
	v_fma_f32 v0, -v0, v172, v171
	v_div_fmas_f32 v0, v0, v170, v172
	v_div_fixup_f32 v147, v0, v147, 1.0
	v_div_scale_f32 v0, s[50:51], v146, v146, 1.0
	v_rcp_f32_e32 v170, v0
	s_nop 0
	v_fma_f32 v171, -v0, v170, 1.0
	v_fmac_f32_e32 v170, v171, v170
	v_div_scale_f32 v171, vcc, 1.0, v146, 1.0
	v_mul_f32_e32 v172, v171, v170
	v_fma_f32 v173, -v0, v172, v171
	v_fmac_f32_e32 v172, v173, v170
	v_fma_f32 v0, -v0, v172, v171
	v_div_fmas_f32 v0, v0, v170, v172
	v_div_fixup_f32 v146, v0, v146, 1.0
	v_mul_f32_e32 v0, 0xbfb8aa3b, v169
	v_exp_f32_e32 v169, v0
	s_nop 0
	v_pk_add_f32 v[168:169], v[168:169], 1.0 op_sel_hi:[1,0]
	s_nop 0
	v_div_scale_f32 v0, s[50:51], v169, v169, 1.0
	v_rcp_f32_e32 v170, v0
	s_nop 0
	v_fma_f32 v171, -v0, v170, 1.0
	v_fmac_f32_e32 v170, v171, v170
	v_div_scale_f32 v171, vcc, 1.0, v169, 1.0
	v_mul_f32_e32 v172, v171, v170
	v_fma_f32 v173, -v0, v172, v171
	v_fmac_f32_e32 v172, v173, v170
	v_fma_f32 v0, -v0, v172, v171
	v_div_fmas_f32 v0, v0, v170, v172
	v_div_fixup_f32 v169, v0, v169, 1.0
	v_div_scale_f32 v0, s[50:51], v168, v168, 1.0
	v_rcp_f32_e32 v170, v0
	s_nop 0
	v_fma_f32 v171, -v0, v170, 1.0
	v_fmac_f32_e32 v170, v171, v170
	v_div_scale_f32 v171, vcc, 1.0, v168, 1.0
	v_mul_f32_e32 v172, v171, v170
	v_fma_f32 v173, -v0, v172, v171
	v_fmac_f32_e32 v172, v173, v170
	v_fma_f32 v0, -v0, v172, v171
	v_div_fmas_f32 v0, v0, v170, v172
	v_div_fixup_f32 v168, v0, v168, 1.0
	v_div_scale_f32 v0, s[50:51], v167, v167, 1.0
	v_rcp_f32_e32 v170, v0
	s_nop 0
	v_fma_f32 v171, -v0, v170, 1.0
	v_fmac_f32_e32 v170, v171, v170
	v_div_scale_f32 v171, vcc, 1.0, v167, 1.0
	v_mul_f32_e32 v172, v171, v170
	v_fma_f32 v173, -v0, v172, v171
	v_fmac_f32_e32 v172, v173, v170
	v_fma_f32 v0, -v0, v172, v171
	v_div_fmas_f32 v0, v0, v170, v172
	v_div_fixup_f32 v167, v0, v167, 1.0
	v_div_scale_f32 v0, s[50:51], v166, v166, 1.0
	v_rcp_f32_e32 v170, v0
	s_nop 0
	v_fma_f32 v171, -v0, v170, 1.0
	v_fmac_f32_e32 v170, v171, v170
	v_div_scale_f32 v171, vcc, 1.0, v166, 1.0
	v_mul_f32_e32 v172, v171, v170
	v_fma_f32 v173, -v0, v172, v171
	v_fmac_f32_e32 v172, v173, v170
	v_fma_f32 v0, -v0, v172, v171
	v_div_fmas_f32 v0, v0, v170, v172
	v_mov_b64_e32 v[170:171], s[20:21]
	v_mad_i64_i32 v[170:171], s[50:51], v180, s31, v[170:171]
	v_lshl_add_u64 v[170:171], v[218:219], 2, v[170:171]
	v_div_fixup_f32 v166, v0, v166, 1.0
	global_store_dwordx4 v[170:171], v[146:149], off
	global_store_dwordx4 v[170:171], v[166:169], off offset:16
.LBB0_697:
	s_or_b64 exec, exec, s[4:5]
	v_and_b32_e32 v170, 15, v240
	v_or_b32_e32 v170, 48, v170
	v_lshlrev_b32_e32 v170, 2, v170
	ds_bpermute_b32 v150, v170, v146
	ds_bpermute_b32 v151, v170, v147
	ds_bpermute_b32 v152, v170, v148
	ds_bpermute_b32 v153, v170, v149
	v_readlane_b32 s4, v254, 26
	v_readlane_b32 s5, v254, 27
	s_nop 4
	s_load_dword s31, s[4:5], 0xc
	s_waitcnt lgkmcnt(0)
	v_add_f32_e32 v0, s31, v153
	s_load_dword s31, s[4:5], 0x0
	s_waitcnt lgkmcnt(0)
	v_add_f32_e32 v171, s31, v150
	v_cmp_eq_u32_e32 vcc, 0, v246
	s_nop 1
	v_cndmask_b32_e32 v0, v0, v171, vcc
	s_load_dword s31, s[4:5], 0x4
	s_waitcnt lgkmcnt(0)
	v_add_f32_e32 v171, s31, v151
	v_cmp_eq_u32_e32 vcc, 1, v246
	s_nop 1
	v_cndmask_b32_e32 v0, v0, v171, vcc
	s_load_dword s31, s[4:5], 0x8
	s_waitcnt lgkmcnt(0)
	v_add_f32_e32 v171, s31, v152
	v_cmp_eq_u32_e32 vcc, 2, v246
	s_nop 1
	v_cndmask_b32_e32 v0, v0, v171, vcc
	v_cmp_nlt_f32_e32 vcc, 0, v0
	s_and_saveexec_b64 s[4:5], vcc
	s_xor_b64 s[4:5], exec, s[4:5]
	s_cbranch_execz .LBB0_680
	v_mul_f32_e32 v146, 0x3fb8aa3b, v0
	v_exp_f32_e32 v146, v146
	s_mov_b32 s31, 0x3f2aaaab
	v_add_f32_e32 v168, 1.0, v146
	v_frexp_mant_f32_e32 v170, v168
	v_cvt_f64_f32_e32 v[166:167], v168
	v_frexp_exp_i32_f64_e32 v166, v[166:167]
	v_cmp_gt_f32_e32 vcc, s31, v170
	v_add_f32_e32 v169, -1.0, v168
	v_sub_f32_e32 v171, v169, v168
	v_subbrev_co_u32_e32 v174, vcc, 0, v166, vcc
	v_sub_u32_e32 v166, 0, v174
	v_sub_f32_e32 v169, v146, v169
	v_add_f32_e32 v171, 1.0, v171
	v_ldexp_f32 v167, v168, v166
	v_add_f32_e32 v169, v169, v171
	v_add_f32_e32 v168, -1.0, v167
	v_add_f32_e32 v170, 1.0, v167
	v_ldexp_f32 v166, v169, v166
	v_add_f32_e32 v169, 1.0, v168
	v_add_f32_e32 v171, -1.0, v170
	v_sub_f32_e32 v169, v167, v169
	v_sub_f32_e32 v167, v167, v171
	v_add_f32_e32 v169, v166, v169
	v_add_f32_e32 v166, v166, v167
	v_add_f32_e32 v175, v170, v166
	v_rcp_f32_e32 v177, v175
	v_sub_f32_e32 v167, v175, v170
	v_sub_f32_e32 v176, v166, v167
	v_add_f32_e32 v167, v168, v169
	v_mul_f32_e32 v179, v167, v177
	v_sub_f32_e32 v166, v167, v168
	v_mul_f32_e32 v168, v175, v179
	v_fma_f32 v170, v179, v175, -v168
	v_fmac_f32_e32 v170, v179, v176
	v_sub_f32_e32 v178, v169, v166
	v_add_f32_e32 v166, v168, v170
	v_sub_f32_e32 v169, v167, v166
	v_pk_add_f32 v[172:173], v[166:167], v[168:169] neg_lo:[0,1] neg_hi:[0,1]
	v_mov_b32_e32 v171, v166
	v_pk_add_f32 v[166:167], v[172:173], v[170:171] neg_lo:[0,1] neg_hi:[0,1]
	s_mov_b32 s31, 0x3f317218
	v_add_f32_e32 v167, v178, v167
	v_add_f32_e32 v166, v166, v167
	v_add_f32_e32 v167, v169, v166
	v_mul_f32_e32 v178, v177, v167
	v_mul_f32_e32 v168, v175, v178
	v_fma_f32 v170, v178, v175, -v168
	v_fmac_f32_e32 v170, v178, v176
	v_sub_f32_e32 v169, v169, v167
	v_add_f32_e32 v175, v166, v169
	v_add_f32_e32 v166, v168, v170
	v_sub_f32_e32 v169, v167, v166
	v_pk_add_f32 v[172:173], v[166:167], v[168:169] neg_lo:[0,1] neg_hi:[0,1]
	v_mov_b32_e32 v171, v166
	v_pk_add_f32 v[166:167], v[172:173], v[170:171] neg_lo:[0,1] neg_hi:[0,1]
	s_nop 0
	v_add_f32_e32 v167, v175, v167
	v_add_f32_e32 v166, v166, v167
	v_add_f32_e32 v167, v179, v178
	v_add_f32_e32 v166, v169, v166
	v_sub_f32_e32 v168, v167, v179
	v_mul_f32_e32 v166, v177, v166
	v_sub_f32_e32 v168, v178, v168
	v_add_f32_e32 v168, v168, v166
	v_add_f32_e32 v170, v167, v168
	v_mul_f32_e32 v171, v170, v170
	v_fmamk_f32 v166, v171, 0x3e9b6dac, v236
	v_fmaak_f32 v205, v171, v166, 0x3f2aaada
	v_cvt_f32_i32_e32 v166, v174
	v_sub_f32_e32 v167, v170, v167
	v_sub_f32_e32 v167, v168, v167
	v_ldexp_f32 v172, v167, 1
	v_mul_f32_e32 v167, v170, v171
	v_ldexp_f32 v169, v170, 1
	v_pk_mul_f32 v[170:171], v[166:167], v[204:205]
	s_nop 0
	v_fma_f32 v168, v166, s31, -v170
	v_fmac_f32_e32 v168, 0xb102e308, v166
	v_pk_add_f32 v[166:167], v[170:171], v[168:169]
	s_mov_b32 s31, 0x7f800000
	v_sub_f32_e32 v169, v167, v169
	v_sub_f32_e32 v169, v171, v169
	v_add_f32_e32 v173, v172, v169
	v_mov_b32_e32 v172, v170
	v_pk_add_f32 v[170:171], v[166:167], v[170:171] neg_lo:[0,1] neg_hi:[0,1]
	v_pk_add_f32 v[174:175], v[166:167], v[172:173]
	v_mov_b32_e32 v169, v166
	v_mov_b32_e32 v171, v175
	v_pk_add_f32 v[176:177], v[168:169], v[170:171] neg_lo:[0,1] neg_hi:[0,1]
	v_pk_add_f32 v[168:169], v[168:169], v[170:171]
	v_mov_b32_e32 v172, v173
	v_pk_add_f32 v[170:171], v[168:169], v[166:167] op_sel:[1,0] op_sel_hi:[0,1] neg_lo:[0,1] neg_hi:[0,1]
	v_pk_add_f32 v[178:179], v[174:175], v[170:171] op_sel_hi:[1,0] neg_lo:[0,1] neg_hi:[0,1]
	v_mov_b32_e32 v174, v175
	v_mov_b32_e32 v175, v169
	v_pk_mov_b32 v[170:171], v[166:167], v[170:171] op_sel:[1,0]
	v_mov_b32_e32 v173, v166
	v_pk_add_f32 v[170:171], v[174:175], v[170:171] neg_lo:[0,1] neg_hi:[0,1]
	v_mov_b32_e32 v178, v176
	v_pk_add_f32 v[166:167], v[172:173], v[170:171] neg_lo:[0,1] neg_hi:[0,1]
	v_mov_b32_e32 v177, v169
	v_pk_add_f32 v[170:171], v[178:179], v[166:167]
	v_cmp_neq_f32_e32 vcc, s31, v146
	v_pk_add_f32 v[172:173], v[170:171], v[170:171] op_sel:[0,1] op_sel_hi:[1,0]
	s_mov_b32 s31, 0x33800000
	v_pk_add_f32 v[168:169], v[168:169], v[172:173] op_sel:[1,0] op_sel_hi:[0,1]
	v_mov_b32_e32 v171, v168
	v_pk_add_f32 v[174:175], v[170:171], v[176:177] neg_lo:[0,1] neg_hi:[0,1]
	v_mov_b32_e32 v167, v172
	v_sub_f32_e32 v169, v170, v174
	v_pk_add_f32 v[166:167], v[166:167], v[174:175] neg_lo:[0,1] neg_hi:[0,1]
	v_sub_f32_e32 v169, v176, v169
	v_add_f32_e32 v166, v166, v169
	v_add_f32_e32 v166, v166, v167
	v_add_f32_e32 v166, v168, v166
	v_cndmask_b32_e32 v166, v237, v166, vcc
	v_cmp_ngt_f32_e32 vcc, -1.0, v146
	s_nop 1
	v_cndmask_b32_e32 v166, v238, v166, vcc
	v_cmp_neq_f32_e32 vcc, -1.0, v146
	s_nop 1
	v_cndmask_b32_e32 v166, v239, v166, vcc
	v_cmp_lt_f32_e64 vcc, |v146|, s31
	s_nop 1
	v_cndmask_b32_e32 v146, v166, v146, vcc
	v_sub_f32_e32 v146, v0, v146

.LBB0_682:
	s_or_b64 exec, exec, s[4:5]
	v_lshlrev_b32_e32 v168, 2, v181
	v_lshlrev_b32_e32 v0, 2, v182
	v_add_u32_e32 v168, v168, v246
	v_ashrrev_i32_e32 v169, 31, v168
	v_lshl_add_u64 v[166:167], s[84:85], 0, v[0:1]
	v_lshlrev_b64 v[170:171], 13, v[168:169]
	v_lshl_add_u64 v[170:171], v[166:167], 0, v[170:171]
	v_readlane_b32 s4, v254, 26
	global_store_dword v[170:171], v146, off
	s_nop 0
	v_add_u32_e32 v166, 0x80, v226
	s_and_saveexec_b64 s[4:5], s[18:19]
	s_cbranch_execnz .LBB0_675

.LBB0_718:
	s_and_saveexec_b64 s[4:5], s[10:11]
	s_xor_b64 s[18:19], exec, s[4:5]
	s_cbranch_execz .LBB0_736
.LBB0_736:
	s_andn2_saveexec_b64 s[4:5], s[18:19]
	s_cbranch_execz .LBB0_738
	s_waitcnt lgkmcnt(0)
	v_mul_f32_e32 v0, 0xbfb8aa3b, v122
	v_exp_f32_e32 v122, v0
	v_mul_f32_e32 v0, 0xbfb8aa3b, v126
	v_exp_f32_e32 v126, v0
	v_mul_f32_e32 v0, 0xbfb8aa3b, v123
	v_exp_f32_e32 v123, v0
	v_mul_f32_e32 v0, 0xbfb8aa3b, v127
	v_exp_f32_e32 v127, v0
	v_mul_f32_e32 v0, 0xbfb8aa3b, v124
	v_exp_f32_e32 v124, v0
	v_mul_f32_e32 v0, 0xbfb8aa3b, v128
	v_exp_f32_e32 v128, v0
	v_mul_f32_e32 v0, 0xbfb8aa3b, v125
	v_exp_f32_e32 v125, v0
	v_pk_add_f32 v[122:123], v[122:123], 1.0 op_sel_hi:[1,0]
	v_pk_add_f32 v[126:127], v[126:127], 1.0 op_sel_hi:[1,0]
	v_pk_add_f32 v[124:125], v[124:125], 1.0 op_sel_hi:[1,0]
	s_nop 0
	v_div_scale_f32 v0, s[18:19], v125, v125, 1.0
	v_rcp_f32_e32 v146, v0
	s_nop 0
	v_fma_f32 v147, -v0, v146, 1.0
	v_fmac_f32_e32 v146, v147, v146
	v_div_scale_f32 v147, vcc, 1.0, v125, 1.0
	v_mul_f32_e32 v148, v147, v146
	v_fma_f32 v149, -v0, v148, v147
	v_fmac_f32_e32 v148, v149, v146
	v_fma_f32 v0, -v0, v148, v147
	v_div_fmas_f32 v0, v0, v146, v148
	v_div_fixup_f32 v125, v0, v125, 1.0
	v_div_scale_f32 v0, s[18:19], v124, v124, 1.0
	v_rcp_f32_e32 v146, v0
	s_nop 0
	v_fma_f32 v147, -v0, v146, 1.0
	v_fmac_f32_e32 v146, v147, v146
	v_div_scale_f32 v147, vcc, 1.0, v124, 1.0
	v_mul_f32_e32 v148, v147, v146
	v_fma_f32 v149, -v0, v148, v147
	v_fmac_f32_e32 v148, v149, v146
	v_fma_f32 v0, -v0, v148, v147
	v_div_fmas_f32 v0, v0, v146, v148
	v_div_fixup_f32 v124, v0, v124, 1.0
	v_div_scale_f32 v0, s[18:19], v123, v123, 1.0
	v_rcp_f32_e32 v146, v0
	s_nop 0
	v_fma_f32 v147, -v0, v146, 1.0
	v_fmac_f32_e32 v146, v147, v146
	v_div_scale_f32 v147, vcc, 1.0, v123, 1.0
	v_mul_f32_e32 v148, v147, v146
	v_fma_f32 v149, -v0, v148, v147
	v_fmac_f32_e32 v148, v149, v146
	v_fma_f32 v0, -v0, v148, v147
	v_div_fmas_f32 v0, v0, v146, v148
	v_div_fixup_f32 v123, v0, v123, 1.0
	v_div_scale_f32 v0, s[18:19], v122, v122, 1.0
	v_rcp_f32_e32 v146, v0
	s_nop 0
	v_fma_f32 v147, -v0, v146, 1.0
	v_fmac_f32_e32 v146, v147, v146
	v_div_scale_f32 v147, vcc, 1.0, v122, 1.0
	v_mul_f32_e32 v148, v147, v146
	v_fma_f32 v149, -v0, v148, v147
	v_fmac_f32_e32 v148, v149, v146
	v_fma_f32 v0, -v0, v148, v147
	v_div_fmas_f32 v0, v0, v146, v148
	v_div_fixup_f32 v122, v0, v122, 1.0
	v_mul_f32_e32 v0, 0xbfb8aa3b, v129
	v_exp_f32_e32 v129, v0
	s_nop 0
	v_pk_add_f32 v[128:129], v[128:129], 1.0 op_sel_hi:[1,0]
	s_nop 0
	v_div_scale_f32 v0, s[18:19], v129, v129, 1.0
	v_rcp_f32_e32 v146, v0
	s_nop 0
	v_fma_f32 v147, -v0, v146, 1.0
	v_fmac_f32_e32 v146, v147, v146
	v_div_scale_f32 v147, vcc, 1.0, v129, 1.0
	v_mul_f32_e32 v148, v147, v146
	v_fma_f32 v149, -v0, v148, v147
	v_fmac_f32_e32 v148, v149, v146
	v_fma_f32 v0, -v0, v148, v147
	v_div_fmas_f32 v0, v0, v146, v148
	v_div_fixup_f32 v129, v0, v129, 1.0
	v_div_scale_f32 v0, s[18:19], v128, v128, 1.0
	v_rcp_f32_e32 v146, v0
	s_nop 0
	v_fma_f32 v147, -v0, v146, 1.0
	v_fmac_f32_e32 v146, v147, v146
	v_div_scale_f32 v147, vcc, 1.0, v128, 1.0
	v_mul_f32_e32 v148, v147, v146
	v_fma_f32 v149, -v0, v148, v147
	v_fmac_f32_e32 v148, v149, v146
	v_fma_f32 v0, -v0, v148, v147
	v_div_fmas_f32 v0, v0, v146, v148
	v_div_fixup_f32 v128, v0, v128, 1.0
	v_div_scale_f32 v0, s[18:19], v127, v127, 1.0
	v_rcp_f32_e32 v146, v0
	s_nop 0
	v_fma_f32 v147, -v0, v146, 1.0
	v_fmac_f32_e32 v146, v147, v146
	v_div_scale_f32 v147, vcc, 1.0, v127, 1.0
	v_mul_f32_e32 v148, v147, v146
	v_fma_f32 v149, -v0, v148, v147
	v_fmac_f32_e32 v148, v149, v146
	v_fma_f32 v0, -v0, v148, v147
	v_div_fmas_f32 v0, v0, v146, v148
	v_div_fixup_f32 v127, v0, v127, 1.0
	v_div_scale_f32 v0, s[18:19], v126, v126, 1.0
	v_rcp_f32_e32 v146, v0
	s_movk_i32 s18, 0x60
	v_fma_f32 v147, -v0, v146, 1.0
	v_fmac_f32_e32 v146, v147, v146
	v_div_scale_f32 v147, vcc, 1.0, v126, 1.0
	v_mul_f32_e32 v148, v147, v146
	v_fma_f32 v149, -v0, v148, v147
	v_fmac_f32_e32 v148, v149, v146
	v_fma_f32 v0, -v0, v148, v147
	v_div_fmas_f32 v0, v0, v146, v148
	v_mov_b64_e32 v[146:147], s[20:21]
	v_mad_i64_i32 v[146:147], s[18:19], v166, s18, v[146:147]
	v_lshl_add_u64 v[146:147], v[218:219], 2, v[146:147]
	v_div_fixup_f32 v126, v0, v126, 1.0
	global_store_dwordx4 v[146:147], v[122:125], off
	global_store_dwordx4 v[146:147], v[126:129], off offset:16
.LBB0_738:
	s_or_b64 exec, exec, s[4:5]
	v_and_b32_e32 v146, 15, v240
	v_or_b32_e32 v146, 48, v146
	v_lshlrev_b32_e32 v146, 2, v146
	ds_bpermute_b32 v126, v146, v122
	ds_bpermute_b32 v127, v146, v123
	ds_bpermute_b32 v128, v146, v124
	ds_bpermute_b32 v129, v146, v125
	v_readlane_b32 s4, v254, 26
	v_readlane_b32 s5, v254, 27
	s_nop 4
	s_load_dword s31, s[4:5], 0xc
	s_waitcnt lgkmcnt(0)
	v_add_f32_e32 v0, s31, v129
	s_load_dword s31, s[4:5], 0x0
	s_waitcnt lgkmcnt(0)
	v_add_f32_e32 v147, s31, v126
	v_cmp_eq_u32_e32 vcc, 0, v246
	s_nop 1
	v_cndmask_b32_e32 v0, v0, v147, vcc
	s_load_dword s31, s[4:5], 0x4
	s_waitcnt lgkmcnt(0)
	v_add_f32_e32 v147, s31, v127
	v_cmp_eq_u32_e32 vcc, 1, v246
	s_nop 1
	v_cndmask_b32_e32 v0, v0, v147, vcc
	s_load_dword s31, s[4:5], 0x8
	s_waitcnt lgkmcnt(0)
	v_add_f32_e32 v147, s31, v128
	v_cmp_eq_u32_e32 vcc, 2, v246
	s_nop 1
	v_cndmask_b32_e32 v0, v0, v147, vcc
	v_cmp_nlt_f32_e32 vcc, 0, v0
	s_and_saveexec_b64 s[4:5], vcc
	s_xor_b64 s[4:5], exec, s[4:5]
	s_cbranch_execz .LBB0_721
	v_mul_f32_e32 v122, 0x3fb8aa3b, v0
	v_exp_f32_e32 v122, v122
	s_mov_b32 s31, 0x3f2aaaab
	v_add_f32_e32 v128, 1.0, v122
	v_frexp_mant_f32_e32 v146, v128
	v_cvt_f64_f32_e32 v[126:127], v128
	v_frexp_exp_i32_f64_e32 v126, v[126:127]
	v_cmp_gt_f32_e32 vcc, s31, v146
	v_add_f32_e32 v129, -1.0, v128
	v_sub_f32_e32 v147, v129, v128
	v_subbrev_co_u32_e32 v150, vcc, 0, v126, vcc
	v_sub_u32_e32 v126, 0, v150
	v_sub_f32_e32 v129, v122, v129
	v_add_f32_e32 v147, 1.0, v147
	v_ldexp_f32 v127, v128, v126
	v_add_f32_e32 v129, v129, v147
	v_add_f32_e32 v128, -1.0, v127
	v_add_f32_e32 v146, 1.0, v127
	v_ldexp_f32 v126, v129, v126
	v_add_f32_e32 v129, 1.0, v128
	v_add_f32_e32 v147, -1.0, v146
	v_sub_f32_e32 v129, v127, v129
	v_sub_f32_e32 v127, v127, v147
	v_add_f32_e32 v129, v126, v129
	v_add_f32_e32 v126, v126, v127
	v_add_f32_e32 v151, v146, v126
	v_rcp_f32_e32 v153, v151
	v_sub_f32_e32 v127, v151, v146
	v_sub_f32_e32 v152, v126, v127
	v_add_f32_e32 v127, v128, v129
	v_mul_f32_e32 v155, v127, v153
	v_sub_f32_e32 v126, v127, v128
	v_mul_f32_e32 v128, v151, v155
	v_fma_f32 v146, v155, v151, -v128
	v_fmac_f32_e32 v146, v155, v152
	v_sub_f32_e32 v154, v129, v126
	v_add_f32_e32 v126, v128, v146
	v_sub_f32_e32 v129, v127, v126
	v_pk_add_f32 v[148:149], v[126:127], v[128:129] neg_lo:[0,1] neg_hi:[0,1]
	v_mov_b32_e32 v147, v126
	v_pk_add_f32 v[126:127], v[148:149], v[146:147] neg_lo:[0,1] neg_hi:[0,1]
	s_mov_b32 s31, 0x3f317218
	v_add_f32_e32 v127, v154, v127
	v_add_f32_e32 v126, v126, v127
	v_add_f32_e32 v127, v129, v126
	v_mul_f32_e32 v154, v153, v127
	v_mul_f32_e32 v128, v151, v154
	v_fma_f32 v146, v154, v151, -v128
	v_fmac_f32_e32 v146, v154, v152
	v_sub_f32_e32 v129, v129, v127
	v_add_f32_e32 v151, v126, v129
	v_add_f32_e32 v126, v128, v146
	v_sub_f32_e32 v129, v127, v126
	v_pk_add_f32 v[148:149], v[126:127], v[128:129] neg_lo:[0,1] neg_hi:[0,1]
	v_mov_b32_e32 v147, v126
	v_pk_add_f32 v[126:127], v[148:149], v[146:147] neg_lo:[0,1] neg_hi:[0,1]
	s_nop 0
	v_add_f32_e32 v127, v151, v127
	v_add_f32_e32 v126, v126, v127
	v_add_f32_e32 v127, v155, v154
	v_add_f32_e32 v126, v129, v126
	v_sub_f32_e32 v128, v127, v155
	v_mul_f32_e32 v126, v153, v126
	v_sub_f32_e32 v128, v154, v128
	v_add_f32_e32 v128, v128, v126
	v_add_f32_e32 v146, v127, v128
	v_mul_f32_e32 v147, v146, v146
	v_fmamk_f32 v126, v147, 0x3e9b6dac, v236
	v_fmaak_f32 v205, v147, v126, 0x3f2aaada
	v_cvt_f32_i32_e32 v126, v150
	v_sub_f32_e32 v127, v146, v127
	v_sub_f32_e32 v127, v128, v127
	v_ldexp_f32 v148, v127, 1
	v_mul_f32_e32 v127, v146, v147
	v_ldexp_f32 v129, v146, 1
	v_pk_mul_f32 v[146:147], v[126:127], v[204:205]
	s_nop 0
	v_fma_f32 v128, v126, s31, -v146
	v_fmac_f32_e32 v128, 0xb102e308, v126
	v_pk_add_f32 v[126:127], v[146:147], v[128:129]
	s_mov_b32 s31, 0x7f800000
	v_sub_f32_e32 v129, v127, v129
	v_sub_f32_e32 v129, v147, v129
	v_add_f32_e32 v149, v148, v129
	v_mov_b32_e32 v148, v146
	v_pk_add_f32 v[146:147], v[126:127], v[146:147] neg_lo:[0,1] neg_hi:[0,1]
	v_pk_add_f32 v[150:151], v[126:127], v[148:149]
	v_mov_b32_e32 v129, v126
	v_mov_b32_e32 v147, v151
	v_pk_add_f32 v[152:153], v[128:129], v[146:147] neg_lo:[0,1] neg_hi:[0,1]
	v_pk_add_f32 v[128:129], v[128:129], v[146:147]
	v_mov_b32_e32 v148, v149
	v_pk_add_f32 v[146:147], v[128:129], v[126:127] op_sel:[1,0] op_sel_hi:[0,1] neg_lo:[0,1] neg_hi:[0,1]
	v_pk_add_f32 v[154:155], v[150:151], v[146:147] op_sel_hi:[1,0] neg_lo:[0,1] neg_hi:[0,1]
	v_mov_b32_e32 v150, v151
	v_mov_b32_e32 v151, v129
	v_pk_mov_b32 v[146:147], v[126:127], v[146:147] op_sel:[1,0]
	v_mov_b32_e32 v149, v126
	v_pk_add_f32 v[146:147], v[150:151], v[146:147] neg_lo:[0,1] neg_hi:[0,1]
	v_mov_b32_e32 v154, v152
	v_pk_add_f32 v[126:127], v[148:149], v[146:147] neg_lo:[0,1] neg_hi:[0,1]
	v_mov_b32_e32 v153, v129
	v_pk_add_f32 v[146:147], v[154:155], v[126:127]
	v_cmp_neq_f32_e32 vcc, s31, v122
	v_pk_add_f32 v[148:149], v[146:147], v[146:147] op_sel:[0,1] op_sel_hi:[1,0]
	s_mov_b32 s31, 0x33800000
	v_pk_add_f32 v[128:129], v[128:129], v[148:149] op_sel:[1,0] op_sel_hi:[0,1]
	v_mov_b32_e32 v147, v128
	v_pk_add_f32 v[150:151], v[146:147], v[152:153] neg_lo:[0,1] neg_hi:[0,1]
	v_mov_b32_e32 v127, v148
	v_sub_f32_e32 v129, v146, v150
	v_pk_add_f32 v[126:127], v[126:127], v[150:151] neg_lo:[0,1] neg_hi:[0,1]
	v_sub_f32_e32 v129, v152, v129
	v_add_f32_e32 v126, v126, v129
	v_add_f32_e32 v126, v126, v127
	v_add_f32_e32 v126, v128, v126
	v_cndmask_b32_e32 v126, v237, v126, vcc
	v_cmp_ngt_f32_e32 vcc, -1.0, v122
	s_nop 1
	v_cndmask_b32_e32 v126, v238, v126, vcc
	v_cmp_neq_f32_e32 vcc, -1.0, v122
	s_nop 1
	v_cndmask_b32_e32 v126, v239, v126, vcc
	v_cmp_lt_f32_e64 vcc, |v122|, s31
	s_nop 1
	v_cndmask_b32_e32 v122, v126, v122, vcc
	v_sub_f32_e32 v122, v0, v122

.LBB0_723:
	s_or_b64 exec, exec, s[4:5]
	v_lshlrev_b32_e32 v128, 2, v156
	v_lshlrev_b32_e32 v0, 2, v157
	v_add_u32_e32 v128, v128, v246
	v_ashrrev_i32_e32 v129, 31, v128
	v_lshl_add_u64 v[126:127], s[84:85], 0, v[0:1]
	v_lshlrev_b64 v[146:147], 13, v[128:129]
	v_lshl_add_u64 v[146:147], v[126:127], 0, v[146:147]
	v_readlane_b32 s4, v254, 26
	global_store_dword v[146:147], v122, off
	s_and_b64 vcc, exec, s[12:13]
	s_cbranch_vccnz .LBB0_742

.LBB0_758:
	s_and_saveexec_b64 s[4:5], s[10:11]
	s_xor_b64 s[18:19], exec, s[4:5]
	s_cbranch_execz .LBB0_776
.LBB0_776:
	s_andn2_saveexec_b64 s[4:5], s[18:19]
	s_cbranch_execz .LBB0_778
	s_waitcnt lgkmcnt(0)
	v_mul_f32_e32 v0, 0xbfb8aa3b, v98
	v_exp_f32_e32 v98, v0
	v_mul_f32_e32 v0, 0xbfb8aa3b, v102
	v_exp_f32_e32 v102, v0
	v_mul_f32_e32 v0, 0xbfb8aa3b, v99
	v_exp_f32_e32 v99, v0
	v_mul_f32_e32 v0, 0xbfb8aa3b, v103
	v_exp_f32_e32 v103, v0
	v_mul_f32_e32 v0, 0xbfb8aa3b, v100
	v_exp_f32_e32 v100, v0
	v_mul_f32_e32 v0, 0xbfb8aa3b, v104
	v_exp_f32_e32 v104, v0
	v_mul_f32_e32 v0, 0xbfb8aa3b, v101
	v_exp_f32_e32 v101, v0
	v_pk_add_f32 v[98:99], v[98:99], 1.0 op_sel_hi:[1,0]
	v_pk_add_f32 v[102:103], v[102:103], 1.0 op_sel_hi:[1,0]
	v_pk_add_f32 v[100:101], v[100:101], 1.0 op_sel_hi:[1,0]
	s_nop 0
	v_div_scale_f32 v0, s[18:19], v101, v101, 1.0
	v_rcp_f32_e32 v122, v0
	s_nop 0
	v_fma_f32 v123, -v0, v122, 1.0
	v_fmac_f32_e32 v122, v123, v122
	v_div_scale_f32 v123, vcc, 1.0, v101, 1.0
	v_mul_f32_e32 v124, v123, v122
	v_fma_f32 v125, -v0, v124, v123
	v_fmac_f32_e32 v124, v125, v122
	v_fma_f32 v0, -v0, v124, v123
	v_div_fmas_f32 v0, v0, v122, v124
	v_div_fixup_f32 v101, v0, v101, 1.0
	v_div_scale_f32 v0, s[18:19], v100, v100, 1.0
	v_rcp_f32_e32 v122, v0
	s_nop 0
	v_fma_f32 v123, -v0, v122, 1.0
	v_fmac_f32_e32 v122, v123, v122
	v_div_scale_f32 v123, vcc, 1.0, v100, 1.0
	v_mul_f32_e32 v124, v123, v122
	v_fma_f32 v125, -v0, v124, v123
	v_fmac_f32_e32 v124, v125, v122
	v_fma_f32 v0, -v0, v124, v123
	v_div_fmas_f32 v0, v0, v122, v124
	v_div_fixup_f32 v100, v0, v100, 1.0
	v_div_scale_f32 v0, s[18:19], v99, v99, 1.0
	v_rcp_f32_e32 v122, v0
	s_nop 0
	v_fma_f32 v123, -v0, v122, 1.0
	v_fmac_f32_e32 v122, v123, v122
	v_div_scale_f32 v123, vcc, 1.0, v99, 1.0
	v_mul_f32_e32 v124, v123, v122
	v_fma_f32 v125, -v0, v124, v123
	v_fmac_f32_e32 v124, v125, v122
	v_fma_f32 v0, -v0, v124, v123
	v_div_fmas_f32 v0, v0, v122, v124
	v_div_fixup_f32 v99, v0, v99, 1.0
	v_div_scale_f32 v0, s[18:19], v98, v98, 1.0
	v_rcp_f32_e32 v122, v0
	s_nop 0
	v_fma_f32 v123, -v0, v122, 1.0
	v_fmac_f32_e32 v122, v123, v122
	v_div_scale_f32 v123, vcc, 1.0, v98, 1.0
	v_mul_f32_e32 v124, v123, v122
	v_fma_f32 v125, -v0, v124, v123
	v_fmac_f32_e32 v124, v125, v122
	v_fma_f32 v0, -v0, v124, v123
	v_div_fmas_f32 v0, v0, v122, v124
	v_div_fixup_f32 v98, v0, v98, 1.0
	v_mul_f32_e32 v0, 0xbfb8aa3b, v105
	v_exp_f32_e32 v105, v0
	s_nop 0
	v_pk_add_f32 v[104:105], v[104:105], 1.0 op_sel_hi:[1,0]
	s_nop 0
	v_div_scale_f32 v0, s[18:19], v105, v105, 1.0
	v_rcp_f32_e32 v122, v0
	s_nop 0
	v_fma_f32 v123, -v0, v122, 1.0
	v_fmac_f32_e32 v122, v123, v122
	v_div_scale_f32 v123, vcc, 1.0, v105, 1.0
	v_mul_f32_e32 v124, v123, v122
	v_fma_f32 v125, -v0, v124, v123
	v_fmac_f32_e32 v124, v125, v122
	v_fma_f32 v0, -v0, v124, v123
	v_div_fmas_f32 v0, v0, v122, v124
	v_div_fixup_f32 v105, v0, v105, 1.0
	v_div_scale_f32 v0, s[18:19], v104, v104, 1.0
	v_rcp_f32_e32 v122, v0
	s_nop 0
	v_fma_f32 v123, -v0, v122, 1.0
	v_fmac_f32_e32 v122, v123, v122
	v_div_scale_f32 v123, vcc, 1.0, v104, 1.0
	v_mul_f32_e32 v124, v123, v122
	v_fma_f32 v125, -v0, v124, v123
	v_fmac_f32_e32 v124, v125, v122
	v_fma_f32 v0, -v0, v124, v123
	v_div_fmas_f32 v0, v0, v122, v124
	v_div_fixup_f32 v104, v0, v104, 1.0
	v_div_scale_f32 v0, s[18:19], v103, v103, 1.0
	v_rcp_f32_e32 v122, v0
	s_nop 0
	v_fma_f32 v123, -v0, v122, 1.0
	v_fmac_f32_e32 v122, v123, v122
	v_div_scale_f32 v123, vcc, 1.0, v103, 1.0
	v_mul_f32_e32 v124, v123, v122
	v_fma_f32 v125, -v0, v124, v123
	v_fmac_f32_e32 v124, v125, v122
	v_fma_f32 v0, -v0, v124, v123
	v_div_fmas_f32 v0, v0, v122, v124
	v_div_fixup_f32 v103, v0, v103, 1.0
	v_div_scale_f32 v0, s[18:19], v102, v102, 1.0
	v_rcp_f32_e32 v122, v0
	s_movk_i32 s18, 0x60
	v_fma_f32 v123, -v0, v122, 1.0
	v_fmac_f32_e32 v122, v123, v122
	v_div_scale_f32 v123, vcc, 1.0, v102, 1.0
	v_mul_f32_e32 v124, v123, v122
	v_fma_f32 v125, -v0, v124, v123
	v_fmac_f32_e32 v124, v125, v122
	v_fma_f32 v0, -v0, v124, v123
	v_div_fmas_f32 v0, v0, v122, v124
	v_mov_b64_e32 v[122:123], s[20:21]
	v_mad_i64_i32 v[122:123], s[18:19], v132, s18, v[122:123]
	v_lshl_add_u64 v[122:123], v[218:219], 2, v[122:123]
	v_div_fixup_f32 v102, v0, v102, 1.0
	global_store_dwordx4 v[122:123], v[98:101], off
	global_store_dwordx4 v[122:123], v[102:105], off offset:16
.LBB0_778:
	s_or_b64 exec, exec, s[4:5]
	v_and_b32_e32 v122, 15, v240
	v_or_b32_e32 v122, 48, v122
	v_lshlrev_b32_e32 v122, 2, v122
	ds_bpermute_b32 v102, v122, v98
	ds_bpermute_b32 v103, v122, v99
	ds_bpermute_b32 v104, v122, v100
	ds_bpermute_b32 v105, v122, v101
	v_readlane_b32 s4, v254, 26
	v_readlane_b32 s5, v254, 27
	s_nop 4
	s_load_dword s31, s[4:5], 0xc
	s_waitcnt lgkmcnt(0)
	v_add_f32_e32 v0, s31, v105
	s_load_dword s31, s[4:5], 0x0
	s_waitcnt lgkmcnt(0)
	v_add_f32_e32 v123, s31, v102
	v_cmp_eq_u32_e32 vcc, 0, v246
	s_nop 1
	v_cndmask_b32_e32 v0, v0, v123, vcc
	s_load_dword s31, s[4:5], 0x4
	s_waitcnt lgkmcnt(0)
	v_add_f32_e32 v123, s31, v103
	v_cmp_eq_u32_e32 vcc, 1, v246
	s_nop 1
	v_cndmask_b32_e32 v0, v0, v123, vcc
	s_load_dword s31, s[4:5], 0x8
	s_waitcnt lgkmcnt(0)
	v_add_f32_e32 v123, s31, v104
	v_cmp_eq_u32_e32 vcc, 2, v246
	s_nop 1
	v_cndmask_b32_e32 v0, v0, v123, vcc
	v_cmp_nlt_f32_e32 vcc, 0, v0
	s_and_saveexec_b64 s[4:5], vcc
	s_xor_b64 s[4:5], exec, s[4:5]
	s_cbranch_execz .LBB0_761
	v_mul_f32_e32 v98, 0x3fb8aa3b, v0
	v_exp_f32_e32 v98, v98
	s_mov_b32 s31, 0x3f2aaaab
	v_add_f32_e32 v104, 1.0, v98
	v_frexp_mant_f32_e32 v122, v104
	v_cvt_f64_f32_e32 v[102:103], v104
	v_frexp_exp_i32_f64_e32 v102, v[102:103]
	v_cmp_gt_f32_e32 vcc, s31, v122
	v_add_f32_e32 v105, -1.0, v104
	v_sub_f32_e32 v123, v105, v104
	v_subbrev_co_u32_e32 v126, vcc, 0, v102, vcc
	v_sub_u32_e32 v102, 0, v126
	v_sub_f32_e32 v105, v98, v105
	v_add_f32_e32 v123, 1.0, v123
	v_ldexp_f32 v103, v104, v102
	v_add_f32_e32 v105, v105, v123
	v_add_f32_e32 v104, -1.0, v103
	v_add_f32_e32 v122, 1.0, v103
	v_ldexp_f32 v102, v105, v102
	v_add_f32_e32 v105, 1.0, v104
	v_add_f32_e32 v123, -1.0, v122
	v_sub_f32_e32 v105, v103, v105
	v_sub_f32_e32 v103, v103, v123
	v_add_f32_e32 v105, v102, v105
	v_add_f32_e32 v102, v102, v103
	v_add_f32_e32 v127, v122, v102
	v_rcp_f32_e32 v129, v127
	v_sub_f32_e32 v103, v127, v122
	v_sub_f32_e32 v128, v102, v103
	v_add_f32_e32 v103, v104, v105
	v_mul_f32_e32 v131, v103, v129
	v_sub_f32_e32 v102, v103, v104
	v_mul_f32_e32 v104, v127, v131
	v_fma_f32 v122, v131, v127, -v104
	v_fmac_f32_e32 v122, v131, v128
	v_sub_f32_e32 v130, v105, v102
	v_add_f32_e32 v102, v104, v122
	v_sub_f32_e32 v105, v103, v102
	v_pk_add_f32 v[124:125], v[102:103], v[104:105] neg_lo:[0,1] neg_hi:[0,1]
	v_mov_b32_e32 v123, v102
	v_pk_add_f32 v[102:103], v[124:125], v[122:123] neg_lo:[0,1] neg_hi:[0,1]
	s_mov_b32 s31, 0x3f317218
	v_add_f32_e32 v103, v130, v103
	v_add_f32_e32 v102, v102, v103
	v_add_f32_e32 v103, v105, v102
	v_mul_f32_e32 v130, v129, v103
	v_mul_f32_e32 v104, v127, v130
	v_fma_f32 v122, v130, v127, -v104
	v_fmac_f32_e32 v122, v130, v128
	v_sub_f32_e32 v105, v105, v103
	v_add_f32_e32 v127, v102, v105
	v_add_f32_e32 v102, v104, v122
	v_sub_f32_e32 v105, v103, v102
	v_pk_add_f32 v[124:125], v[102:103], v[104:105] neg_lo:[0,1] neg_hi:[0,1]
	v_mov_b32_e32 v123, v102
	v_pk_add_f32 v[102:103], v[124:125], v[122:123] neg_lo:[0,1] neg_hi:[0,1]
	s_nop 0
	v_add_f32_e32 v103, v127, v103
	v_add_f32_e32 v102, v102, v103
	v_add_f32_e32 v103, v131, v130
	v_add_f32_e32 v102, v105, v102
	v_sub_f32_e32 v104, v103, v131
	v_mul_f32_e32 v102, v129, v102
	v_sub_f32_e32 v104, v130, v104
	v_add_f32_e32 v104, v104, v102
	v_add_f32_e32 v122, v103, v104
	v_mul_f32_e32 v123, v122, v122
	v_fmamk_f32 v102, v123, 0x3e9b6dac, v236
	v_fmaak_f32 v205, v123, v102, 0x3f2aaada
	v_cvt_f32_i32_e32 v102, v126
	v_sub_f32_e32 v103, v122, v103
	v_sub_f32_e32 v103, v104, v103
	v_ldexp_f32 v124, v103, 1
	v_mul_f32_e32 v103, v122, v123
	v_ldexp_f32 v105, v122, 1
	v_pk_mul_f32 v[122:123], v[102:103], v[204:205]
	s_nop 0
	v_fma_f32 v104, v102, s31, -v122
	v_fmac_f32_e32 v104, 0xb102e308, v102
	v_pk_add_f32 v[102:103], v[122:123], v[104:105]
	s_mov_b32 s31, 0x7f800000
	v_sub_f32_e32 v105, v103, v105
	v_sub_f32_e32 v105, v123, v105
	v_add_f32_e32 v125, v124, v105
	v_mov_b32_e32 v124, v122
	v_pk_add_f32 v[122:123], v[102:103], v[122:123] neg_lo:[0,1] neg_hi:[0,1]
	v_pk_add_f32 v[126:127], v[102:103], v[124:125]
	v_mov_b32_e32 v105, v102
	v_mov_b32_e32 v123, v127
	v_pk_add_f32 v[128:129], v[104:105], v[122:123] neg_lo:[0,1] neg_hi:[0,1]
	v_pk_add_f32 v[104:105], v[104:105], v[122:123]
	v_mov_b32_e32 v124, v125
	v_pk_add_f32 v[122:123], v[104:105], v[102:103] op_sel:[1,0] op_sel_hi:[0,1] neg_lo:[0,1] neg_hi:[0,1]
	v_pk_add_f32 v[130:131], v[126:127], v[122:123] op_sel_hi:[1,0] neg_lo:[0,1] neg_hi:[0,1]
	v_mov_b32_e32 v126, v127
	v_mov_b32_e32 v127, v105
	v_pk_mov_b32 v[122:123], v[102:103], v[122:123] op_sel:[1,0]
	v_mov_b32_e32 v125, v102
	v_pk_add_f32 v[122:123], v[126:127], v[122:123] neg_lo:[0,1] neg_hi:[0,1]
	v_mov_b32_e32 v130, v128
	v_pk_add_f32 v[102:103], v[124:125], v[122:123] neg_lo:[0,1] neg_hi:[0,1]
	v_mov_b32_e32 v129, v105
	v_pk_add_f32 v[122:123], v[130:131], v[102:103]
	v_cmp_neq_f32_e32 vcc, s31, v98
	v_pk_add_f32 v[124:125], v[122:123], v[122:123] op_sel:[0,1] op_sel_hi:[1,0]
	s_mov_b32 s31, 0x33800000
	v_pk_add_f32 v[104:105], v[104:105], v[124:125] op_sel:[1,0] op_sel_hi:[0,1]
	v_mov_b32_e32 v123, v104
	v_pk_add_f32 v[126:127], v[122:123], v[128:129] neg_lo:[0,1] neg_hi:[0,1]
	v_mov_b32_e32 v103, v124
	v_sub_f32_e32 v105, v122, v126
	v_pk_add_f32 v[102:103], v[102:103], v[126:127] neg_lo:[0,1] neg_hi:[0,1]
	v_sub_f32_e32 v105, v128, v105
	v_add_f32_e32 v102, v102, v105
	v_add_f32_e32 v102, v102, v103
	v_add_f32_e32 v102, v104, v102
	v_cndmask_b32_e32 v102, v237, v102, vcc
	v_cmp_ngt_f32_e32 vcc, -1.0, v98
	s_nop 1
	v_cndmask_b32_e32 v102, v238, v102, vcc
	v_cmp_neq_f32_e32 vcc, -1.0, v98
	s_nop 1
	v_cndmask_b32_e32 v102, v239, v102, vcc
	v_cmp_lt_f32_e64 vcc, |v98|, s31
	s_nop 1
	v_cndmask_b32_e32 v98, v102, v98, vcc
	v_sub_f32_e32 v98, v0, v98

.LBB0_763:
	s_or_b64 exec, exec, s[4:5]
	v_lshlrev_b32_e32 v104, 2, v133
	v_lshlrev_b32_e32 v0, 2, v134
	v_add_u32_e32 v104, v104, v246
	v_ashrrev_i32_e32 v105, 31, v104
	v_lshl_add_u64 v[102:103], s[84:85], 0, v[0:1]
	v_lshlrev_b64 v[122:123], 13, v[104:105]
	v_lshl_add_u64 v[122:123], v[102:103], 0, v[122:123]
	v_readlane_b32 s4, v254, 26
	global_store_dword v[122:123], v98, off
	s_and_b64 vcc, exec, s[12:13]
	s_cbranch_vccnz .LBB0_782

.LBB0_798:
	s_and_saveexec_b64 s[4:5], s[10:11]
	s_xor_b64 s[18:19], exec, s[4:5]
	s_cbranch_execz .LBB0_816
.LBB0_816:
	s_andn2_saveexec_b64 s[4:5], s[18:19]
	s_cbranch_execz .LBB0_818
	s_waitcnt lgkmcnt(0)
	v_mul_f32_e32 v0, 0xbfb8aa3b, v74
	v_exp_f32_e32 v74, v0
	v_mul_f32_e32 v0, 0xbfb8aa3b, v78
	v_exp_f32_e32 v78, v0
	v_mul_f32_e32 v0, 0xbfb8aa3b, v75
	v_exp_f32_e32 v75, v0
	v_mul_f32_e32 v0, 0xbfb8aa3b, v79
	v_exp_f32_e32 v79, v0
	v_mul_f32_e32 v0, 0xbfb8aa3b, v76
	v_exp_f32_e32 v76, v0
	v_mul_f32_e32 v0, 0xbfb8aa3b, v80
	v_exp_f32_e32 v80, v0
	v_mul_f32_e32 v0, 0xbfb8aa3b, v77
	v_exp_f32_e32 v77, v0
	v_pk_add_f32 v[74:75], v[74:75], 1.0 op_sel_hi:[1,0]
	v_pk_add_f32 v[78:79], v[78:79], 1.0 op_sel_hi:[1,0]
	v_pk_add_f32 v[76:77], v[76:77], 1.0 op_sel_hi:[1,0]
	s_nop 0
	v_div_scale_f32 v0, s[18:19], v77, v77, 1.0
	v_rcp_f32_e32 v98, v0
	s_nop 0
	v_fma_f32 v99, -v0, v98, 1.0
	v_fmac_f32_e32 v98, v99, v98
	v_div_scale_f32 v99, vcc, 1.0, v77, 1.0
	v_mul_f32_e32 v100, v99, v98
	v_fma_f32 v101, -v0, v100, v99
	v_fmac_f32_e32 v100, v101, v98
	v_fma_f32 v0, -v0, v100, v99
	v_div_fmas_f32 v0, v0, v98, v100
	v_div_fixup_f32 v77, v0, v77, 1.0
	v_div_scale_f32 v0, s[18:19], v76, v76, 1.0
	v_rcp_f32_e32 v98, v0
	s_nop 0
	v_fma_f32 v99, -v0, v98, 1.0
	v_fmac_f32_e32 v98, v99, v98
	v_div_scale_f32 v99, vcc, 1.0, v76, 1.0
	v_mul_f32_e32 v100, v99, v98
	v_fma_f32 v101, -v0, v100, v99
	v_fmac_f32_e32 v100, v101, v98
	v_fma_f32 v0, -v0, v100, v99
	v_div_fmas_f32 v0, v0, v98, v100
	v_div_fixup_f32 v76, v0, v76, 1.0
	v_div_scale_f32 v0, s[18:19], v75, v75, 1.0
	v_rcp_f32_e32 v98, v0
	s_nop 0
	v_fma_f32 v99, -v0, v98, 1.0
	v_fmac_f32_e32 v98, v99, v98
	v_div_scale_f32 v99, vcc, 1.0, v75, 1.0
	v_mul_f32_e32 v100, v99, v98
	v_fma_f32 v101, -v0, v100, v99
	v_fmac_f32_e32 v100, v101, v98
	v_fma_f32 v0, -v0, v100, v99
	v_div_fmas_f32 v0, v0, v98, v100
	v_div_fixup_f32 v75, v0, v75, 1.0
	v_div_scale_f32 v0, s[18:19], v74, v74, 1.0
	v_rcp_f32_e32 v98, v0
	s_nop 0
	v_fma_f32 v99, -v0, v98, 1.0
	v_fmac_f32_e32 v98, v99, v98
	v_div_scale_f32 v99, vcc, 1.0, v74, 1.0
	v_mul_f32_e32 v100, v99, v98
	v_fma_f32 v101, -v0, v100, v99
	v_fmac_f32_e32 v100, v101, v98
	v_fma_f32 v0, -v0, v100, v99
	v_div_fmas_f32 v0, v0, v98, v100
	v_div_fixup_f32 v74, v0, v74, 1.0
	v_mul_f32_e32 v0, 0xbfb8aa3b, v81
	v_exp_f32_e32 v81, v0
	s_nop 0
	v_pk_add_f32 v[80:81], v[80:81], 1.0 op_sel_hi:[1,0]
	s_nop 0
	v_div_scale_f32 v0, s[18:19], v81, v81, 1.0
	v_rcp_f32_e32 v98, v0
	s_nop 0
	v_fma_f32 v99, -v0, v98, 1.0
	v_fmac_f32_e32 v98, v99, v98
	v_div_scale_f32 v99, vcc, 1.0, v81, 1.0
	v_mul_f32_e32 v100, v99, v98
	v_fma_f32 v101, -v0, v100, v99
	v_fmac_f32_e32 v100, v101, v98
	v_fma_f32 v0, -v0, v100, v99
	v_div_fmas_f32 v0, v0, v98, v100
	v_div_fixup_f32 v81, v0, v81, 1.0
	v_div_scale_f32 v0, s[18:19], v80, v80, 1.0
	v_rcp_f32_e32 v98, v0
	s_nop 0
	v_fma_f32 v99, -v0, v98, 1.0
	v_fmac_f32_e32 v98, v99, v98
	v_div_scale_f32 v99, vcc, 1.0, v80, 1.0
	v_mul_f32_e32 v100, v99, v98
	v_fma_f32 v101, -v0, v100, v99
	v_fmac_f32_e32 v100, v101, v98
	v_fma_f32 v0, -v0, v100, v99
	v_div_fmas_f32 v0, v0, v98, v100
	v_div_fixup_f32 v80, v0, v80, 1.0
	v_div_scale_f32 v0, s[18:19], v79, v79, 1.0
	v_rcp_f32_e32 v98, v0
	s_nop 0
	v_fma_f32 v99, -v0, v98, 1.0
	v_fmac_f32_e32 v98, v99, v98
	v_div_scale_f32 v99, vcc, 1.0, v79, 1.0
	v_mul_f32_e32 v100, v99, v98
	v_fma_f32 v101, -v0, v100, v99
	v_fmac_f32_e32 v100, v101, v98
	v_fma_f32 v0, -v0, v100, v99
	v_div_fmas_f32 v0, v0, v98, v100
	v_div_fixup_f32 v79, v0, v79, 1.0
	v_div_scale_f32 v0, s[18:19], v78, v78, 1.0
	v_rcp_f32_e32 v98, v0
	s_movk_i32 s18, 0x60
	v_fma_f32 v99, -v0, v98, 1.0
	v_fmac_f32_e32 v98, v99, v98
	v_div_scale_f32 v99, vcc, 1.0, v78, 1.0
	v_mul_f32_e32 v100, v99, v98
	v_fma_f32 v101, -v0, v100, v99
	v_fmac_f32_e32 v100, v101, v98
	v_fma_f32 v0, -v0, v100, v99
	v_div_fmas_f32 v0, v0, v98, v100
	v_mov_b64_e32 v[98:99], s[20:21]
	v_mad_i64_i32 v[98:99], s[18:19], v108, s18, v[98:99]
	v_lshl_add_u64 v[98:99], v[218:219], 2, v[98:99]
	v_div_fixup_f32 v78, v0, v78, 1.0
	global_store_dwordx4 v[98:99], v[74:77], off
	global_store_dwordx4 v[98:99], v[78:81], off offset:16
.LBB0_818:
	s_or_b64 exec, exec, s[4:5]
	v_and_b32_e32 v98, 15, v240
	v_or_b32_e32 v98, 48, v98
	v_lshlrev_b32_e32 v98, 2, v98
	ds_bpermute_b32 v78, v98, v74
	ds_bpermute_b32 v79, v98, v75
	ds_bpermute_b32 v80, v98, v76
	ds_bpermute_b32 v81, v98, v77
	v_readlane_b32 s4, v254, 26
	v_readlane_b32 s5, v254, 27
	s_nop 4
	s_load_dword s31, s[4:5], 0xc
	s_waitcnt lgkmcnt(0)
	v_add_f32_e32 v0, s31, v81
	s_load_dword s31, s[4:5], 0x0
	s_waitcnt lgkmcnt(0)
	v_add_f32_e32 v99, s31, v78
	v_cmp_eq_u32_e32 vcc, 0, v246
	s_nop 1
	v_cndmask_b32_e32 v0, v0, v99, vcc
	s_load_dword s31, s[4:5], 0x4
	s_waitcnt lgkmcnt(0)
	v_add_f32_e32 v99, s31, v79
	v_cmp_eq_u32_e32 vcc, 1, v246
	s_nop 1
	v_cndmask_b32_e32 v0, v0, v99, vcc
	s_load_dword s31, s[4:5], 0x8
	s_waitcnt lgkmcnt(0)
	v_add_f32_e32 v99, s31, v80
	v_cmp_eq_u32_e32 vcc, 2, v246
	s_nop 1
	v_cndmask_b32_e32 v0, v0, v99, vcc
	v_cmp_nlt_f32_e32 vcc, 0, v0
	s_and_saveexec_b64 s[4:5], vcc
	s_xor_b64 s[4:5], exec, s[4:5]
	s_cbranch_execz .LBB0_801
	v_mul_f32_e32 v74, 0x3fb8aa3b, v0
	v_exp_f32_e32 v74, v74
	s_mov_b32 s31, 0x3f2aaaab
	v_add_f32_e32 v80, 1.0, v74
	v_frexp_mant_f32_e32 v98, v80
	v_cvt_f64_f32_e32 v[78:79], v80
	v_frexp_exp_i32_f64_e32 v78, v[78:79]
	v_cmp_gt_f32_e32 vcc, s31, v98
	v_add_f32_e32 v81, -1.0, v80
	v_sub_f32_e32 v99, v81, v80
	v_subbrev_co_u32_e32 v102, vcc, 0, v78, vcc
	v_sub_u32_e32 v78, 0, v102
	v_sub_f32_e32 v81, v74, v81
	v_add_f32_e32 v99, 1.0, v99
	v_ldexp_f32 v79, v80, v78
	v_add_f32_e32 v81, v81, v99
	v_add_f32_e32 v80, -1.0, v79
	v_add_f32_e32 v98, 1.0, v79
	v_ldexp_f32 v78, v81, v78
	v_add_f32_e32 v81, 1.0, v80
	v_add_f32_e32 v99, -1.0, v98
	v_sub_f32_e32 v81, v79, v81
	v_sub_f32_e32 v79, v79, v99
	v_add_f32_e32 v81, v78, v81
	v_add_f32_e32 v78, v78, v79
	v_add_f32_e32 v103, v98, v78
	v_rcp_f32_e32 v105, v103
	v_sub_f32_e32 v79, v103, v98
	v_sub_f32_e32 v104, v78, v79
	v_add_f32_e32 v79, v80, v81
	v_mul_f32_e32 v107, v79, v105
	v_sub_f32_e32 v78, v79, v80
	v_mul_f32_e32 v80, v103, v107
	v_fma_f32 v98, v107, v103, -v80
	v_fmac_f32_e32 v98, v107, v104
	v_sub_f32_e32 v106, v81, v78
	v_add_f32_e32 v78, v80, v98
	v_sub_f32_e32 v81, v79, v78
	v_pk_add_f32 v[100:101], v[78:79], v[80:81] neg_lo:[0,1] neg_hi:[0,1]
	v_mov_b32_e32 v99, v78
	v_pk_add_f32 v[78:79], v[100:101], v[98:99] neg_lo:[0,1] neg_hi:[0,1]
	s_mov_b32 s31, 0x3f317218
	v_add_f32_e32 v79, v106, v79
	v_add_f32_e32 v78, v78, v79
	v_add_f32_e32 v79, v81, v78
	v_mul_f32_e32 v106, v105, v79
	v_mul_f32_e32 v80, v103, v106
	v_fma_f32 v98, v106, v103, -v80
	v_fmac_f32_e32 v98, v106, v104
	v_sub_f32_e32 v81, v81, v79
	v_add_f32_e32 v103, v78, v81
	v_add_f32_e32 v78, v80, v98
	v_sub_f32_e32 v81, v79, v78
	v_pk_add_f32 v[100:101], v[78:79], v[80:81] neg_lo:[0,1] neg_hi:[0,1]
	v_mov_b32_e32 v99, v78
	v_pk_add_f32 v[78:79], v[100:101], v[98:99] neg_lo:[0,1] neg_hi:[0,1]
	s_nop 0
	v_add_f32_e32 v79, v103, v79
	v_add_f32_e32 v78, v78, v79
	v_add_f32_e32 v79, v107, v106
	v_add_f32_e32 v78, v81, v78
	v_sub_f32_e32 v80, v79, v107
	v_mul_f32_e32 v78, v105, v78
	v_sub_f32_e32 v80, v106, v80
	v_add_f32_e32 v80, v80, v78
	v_add_f32_e32 v98, v79, v80
	v_mul_f32_e32 v99, v98, v98
	v_fmamk_f32 v78, v99, 0x3e9b6dac, v236
	v_fmaak_f32 v205, v99, v78, 0x3f2aaada
	v_cvt_f32_i32_e32 v78, v102
	v_sub_f32_e32 v79, v98, v79
	v_sub_f32_e32 v79, v80, v79
	v_ldexp_f32 v100, v79, 1
	v_mul_f32_e32 v79, v98, v99
	v_ldexp_f32 v81, v98, 1
	v_pk_mul_f32 v[98:99], v[78:79], v[204:205]
	s_nop 0
	v_fma_f32 v80, v78, s31, -v98
	v_fmac_f32_e32 v80, 0xb102e308, v78
	v_pk_add_f32 v[78:79], v[98:99], v[80:81]
	s_mov_b32 s31, 0x7f800000
	v_sub_f32_e32 v81, v79, v81
	v_sub_f32_e32 v81, v99, v81
	v_add_f32_e32 v101, v100, v81
	v_mov_b32_e32 v100, v98
	v_pk_add_f32 v[98:99], v[78:79], v[98:99] neg_lo:[0,1] neg_hi:[0,1]
	v_pk_add_f32 v[102:103], v[78:79], v[100:101]
	v_mov_b32_e32 v81, v78
	v_mov_b32_e32 v99, v103
	v_pk_add_f32 v[104:105], v[80:81], v[98:99] neg_lo:[0,1] neg_hi:[0,1]
	v_pk_add_f32 v[80:81], v[80:81], v[98:99]
	v_mov_b32_e32 v100, v101
	v_pk_add_f32 v[98:99], v[80:81], v[78:79] op_sel:[1,0] op_sel_hi:[0,1] neg_lo:[0,1] neg_hi:[0,1]
	v_pk_add_f32 v[106:107], v[102:103], v[98:99] op_sel_hi:[1,0] neg_lo:[0,1] neg_hi:[0,1]
	v_mov_b32_e32 v102, v103
	v_mov_b32_e32 v103, v81
	v_pk_mov_b32 v[98:99], v[78:79], v[98:99] op_sel:[1,0]
	v_mov_b32_e32 v101, v78
	v_pk_add_f32 v[98:99], v[102:103], v[98:99] neg_lo:[0,1] neg_hi:[0,1]
	v_mov_b32_e32 v106, v104
	v_pk_add_f32 v[78:79], v[100:101], v[98:99] neg_lo:[0,1] neg_hi:[0,1]
	v_mov_b32_e32 v105, v81
	v_pk_add_f32 v[98:99], v[106:107], v[78:79]
	v_cmp_neq_f32_e32 vcc, s31, v74
	v_pk_add_f32 v[100:101], v[98:99], v[98:99] op_sel:[0,1] op_sel_hi:[1,0]
	s_mov_b32 s31, 0x33800000
	v_pk_add_f32 v[80:81], v[80:81], v[100:101] op_sel:[1,0] op_sel_hi:[0,1]
	v_mov_b32_e32 v99, v80
	v_pk_add_f32 v[102:103], v[98:99], v[104:105] neg_lo:[0,1] neg_hi:[0,1]
	v_mov_b32_e32 v79, v100
	v_sub_f32_e32 v81, v98, v102
	v_pk_add_f32 v[78:79], v[78:79], v[102:103] neg_lo:[0,1] neg_hi:[0,1]
	v_sub_f32_e32 v81, v104, v81
	v_add_f32_e32 v78, v78, v81
	v_add_f32_e32 v78, v78, v79
	v_add_f32_e32 v78, v80, v78
	v_cndmask_b32_e32 v78, v237, v78, vcc
	v_cmp_ngt_f32_e32 vcc, -1.0, v74
	s_nop 1
	v_cndmask_b32_e32 v78, v238, v78, vcc
	v_cmp_neq_f32_e32 vcc, -1.0, v74
	s_nop 1
	v_cndmask_b32_e32 v78, v239, v78, vcc
	v_cmp_lt_f32_e64 vcc, |v74|, s31
	s_nop 1
	v_cndmask_b32_e32 v74, v78, v74, vcc
	v_sub_f32_e32 v74, v0, v74

.LBB0_803:
	s_or_b64 exec, exec, s[4:5]
	v_lshlrev_b32_e32 v80, 2, v109
	v_lshlrev_b32_e32 v0, 2, v110
	v_add_u32_e32 v80, v80, v246
	v_ashrrev_i32_e32 v81, 31, v80
	v_lshl_add_u64 v[78:79], s[84:85], 0, v[0:1]
	v_lshlrev_b64 v[98:99], 13, v[80:81]
	v_lshl_add_u64 v[98:99], v[78:79], 0, v[98:99]
	v_readlane_b32 s4, v254, 26
	global_store_dword v[98:99], v74, off
	s_and_b64 vcc, exec, s[12:13]
	s_cbranch_vccnz .LBB0_822
